# hand-written attention phase: ping-pong wave halves, 4-slot LDS ring, no permlane via natural V key order
# speedup vs baseline: 1.0833x; 1.0833x over previous
; __device__ void phase_attn(const Params& p, char* lds) {
;     ...
;   const int tid = threadIdx.x, wid = tid >> 6, lane = tid & 63, r32 = lane & 31, hi = lane >> 5;
;   char* V_lds = lds; char* K_lds = lds + AT_KOFF;
;   float* wsl = (float*)(lds + AT_WOFF) + wid * 64; float* li_l = wsl; float* al_l = wsl + 32;
;   const int skey = tid >> 3, sc8 = (tid & 7) * 8;
;   const int pkey = (tid & 255) >> 2, pc8 = (tid & 3) * 8;
;   const int vst = v_st(skey, sc8), kst = skey * AT_KROW + sc8 * 2, pst = pkey * AT_KROW + (64 + pc8) * 2;
;   const int vb0 = (int)(uintptr_t)V_lds + v_rd_base(lane);
;   const int nitems = NB * 16 * 32;
;   const int xcd = blockIdx.x & 7, slot = blockIdx.x >> 3, per = gridDim.x >> 3;
;   for (int it = slot; it < nitems / 8; it += per) {
;     const int pair = (it >> 5) * 8 + xcd, qblk = it & 31;
;     const int b = pair >> 4, h = pair & 15;
;     const size_t row0 = (size_t)b * TL;
;     const size_t qrow = row0 + qblk * 256 + wid * 32 + r32;
;     const bf16_t* Kh = KVg + row0 * 2048 + h * 128;
;     const bf16_t* Kp = KPg + row0 * 32;
;     float m_reg = 0.f, l_reg = 0.f;
;     f32x16 o[2];
; #pragma unroll
;     for (int dd = 0; dd < 2; ++dd)
; #pragma unroll
;       for (int r = 0; r < 16; ++r) o[dd][r] = 0.f;
;     bf16x8 qr[6];
;     {
;       const bf16_t* Qw = Qg + qrow * 1536 + h * 96 + hi * 8;
; #pragma unroll
;       for (int d0 = 0; d0 < 6; ++d0) qr[d0] = *(const bf16x8*)(Qw + d0 * 16);
;       const int t = qblk * 256 + wid * 32 + r32;
;       const f32x2* tb = rope + (hi ? (t & 63) : (t >> 6)) * 8;
;       const u32x4 x1 = *(const u32x4*)&qr[4], x2 = *(const u32x4*)&qr[5];
;       u32x4 n1, n2;
; #pragma unroll
;       for (int q = 0; q < 4; ++q) {
;         const f32x2 csA = tb[2 * q], csB = tb[2 * q + 1];
;         const float a0 = lo16(x1[q]), a1 = hi16(x1[q]), b0 = lo16(x2[q]), b1 = hi16(x2[q]);
;         n1[q] = cvtpk(a0 * csA[0] - b0 * csA[1], a1 * csB[0] - b1 * csB[1]);
;         n2[q] = cvtpk(a0 * csA[1] + b0 * csA[0], a1 * csB[1] + b1 * csB[0]);
;       }
;       qr[4] = *(bf16x8*)&n1; qr[5] = *(bf16x8*)&n2;
;     }
;     struct { bf16x8 vs, ks, ps; } sr_[2];
;     ...
;     f32x16 pA0, pA1, pB0, pB1; float alA, alB; bf16x8 pa0, pa1, pa2, pa3;
;     constexpr int NT = TL / 64;
;     SLOAD(0, 0); asm volatile("s_waitcnt vmcnt(0)" ::: "memory"); SWRITE(0, 0); __syncthreads();
.LBB0_991:
	s_or_b64 exec, exec, s[4:5]
	s_cmpk_gt_u32 s3, 0xfff
	s_waitcnt vmcnt(7)
	v_and_b32_e32 v128, 56, v183
	v_lshlrev_b32_e32 v168, 11, v161
	s_barrier
	v_and_b32_e32 v175, 63, v178
	v_and_b32_e32 v183, 31, v178
	v_lshrrev_b32_e32 v228, 5, v175
	v_readfirstlane_b32 s14, v178
	v_lshrrev_b32_e32 v229, 3, v178
	v_and_b32_e32 v230, 7, v178
	s_lshr_b32 s14, s14, 6
	s_lshr_b32 s15, s14, 2
	s_and_b32 s43, s3, 7
	s_mov_b32 s23, 0x4138aa3b
	v_lshlrev_b32_e32 v129, 4, v230
	v_lshl_or_b32 v129, v229, 12, v129
	v_mul_u32_u24_e32 v167, 0xd0, v229
	v_lshl_add_u32 v167, v230, 4, v167
	v_add_u32_e32 v167, 0x10000, v167
	v_lshrrev_b32_e32 v131, 3, v229
	v_lshlrev_b32_e32 v131, 11, v131
	v_lshrrev_b32_e32 v174, 2, v230
	v_lshl_or_b32 v131, v174, 9, v131
	v_and_b32_e32 v174, 7, v229
	v_lshl_or_b32 v131, v174, 6, v131
	v_and_b32_e32 v174, 3, v178
	v_lshl_or_b32 v131, v174, 4, v131
	v_bfe_u32 v229, v178, 2, 6
	v_lshlrev_b32_e32 v130, 4, v174
	v_lshl_or_b32 v130, v229, 6, v130
	v_mul_u32_u24_e32 v169, 0xd0, v229
	v_lshl_add_u32 v169, v174, 4, v169
	v_add_u32_e32 v169, 0x10080, v169
	v_mul_u32_u24_e32 v170, 0xd0, v183
	v_lshl_add_u32 v170, v228, 4, v170
	v_add_u32_e32 v170, 0x10000, v170
	v_and_b32_e32 v171, 3, v175
	v_lshlrev_b32_e32 v171, 3, v171
	v_bfe_u32 v174, v175, 2, 2
	v_lshl_or_b32 v171, v174, 6, v171
	v_bfe_u32 v174, v175, 4, 1
	v_lshl_or_b32 v171, v174, 5, v171
	v_lshl_or_b32 v171, v228, 8, v171
	s_lshl_b32 s16, s14, 5
	v_add_u32_e32 v174, s16, v183
	v_mul_u32_u24_e32 v234, 0xc00, v174
	v_lshl_add_u32 v234, v228, 4, v234
	v_lshlrev_b32_e32 v235, 2, v228
	v_add_u32_e32 v235, s16, v235
	v_lshlrev_b32_e32 v235, 11, v235
	v_lshl_add_u32 v235, v183, 1, v235
	s_lshl_b32 s17, s14, 8
	s_add_i32 s17, s17, 0x1d000
	v_lshl_add_u32 v244, v183, 2, s17
	v_lshl_add_u32 v245, v228, 4, s17
	s_add_u32 s34, s86, 0x3d796000
	s_addc_u32 s35, s87, 0
	s_lshr_b32 s12, s3, 3
.Lat_item:
	s_lshr_b32 s16, s12, 5
	s_lshl_b32 s16, s16, 3
	s_add_i32 s16, s16, s43
	s_and_b32 s20, s12, 31
	s_lshr_b32 s22, s16, 4
	s_and_b32 s21, s16, 15
	s_mul_i32 s17, s22, 0x2100000
	s_lshl_b32 s18, s21, 8
	s_add_i32 s17, s17, s18
	s_add_u32 s17, s17, 0x29400000
	s_add_u32 s4, s86, s17
	s_addc_u32 s5, s87, 0
	s_mul_i32 s17, s22, 0x84000
	s_add_u32 s17, s17, 0x1de80000
	s_add_u32 s6, s86, s17
	s_addc_u32 s7, s87, 0
	s_mul_i32 s17, s22, 0x2100
	s_lshl_b32 s18, s20, 8
	s_add_i32 s17, s17, s18
	s_mul_i32 s18, s17, 0xc00
	s_mul_i32 s19, s21, 0xc0
	s_add_i32 s18, s18, s19
	s_add_u32 s18, s18, 0x8400000
	s_add_u32 s10, s86, s18
	s_addc_u32 s11, s87, 0
	s_lshl_b32 s18, s17, 11
	s_lshl_b32 s19, s21, 7
	s_add_i32 s18, s18, s19
	s_add_u32 s18, s18, 0x21000000
	s_add_u32 s28, s86, s18
	s_addc_u32 s29, s87, 0
	global_load_dwordx4 v[80:83], v234, s[10:11] offset:0
	global_load_dwordx4 v[84:87], v234, s[10:11] offset:32
	global_load_dwordx4 v[88:91], v234, s[10:11] offset:64
	global_load_dwordx4 v[92:95], v234, s[10:11] offset:96
	global_load_dwordx4 v[96:99], v234, s[10:11] offset:128
	global_load_dwordx4 v[100:103], v234, s[10:11] offset:160
	s_and_b32 s16, s14, 1
	s_lshl_b32 s16, s16, 5
	v_and_b32_e32 v183, 31, v178
	v_add_u32_e32 v183, s16, v183
	v_lshlrev_b32_e32 v183, 6, v183
	s_lshl_b32 s16, s20, 2
	s_lshr_b32 s17, s14, 1
	s_add_i32 s16, s16, s17
	s_lshl_b32 s16, s16, 6
	v_mov_b32_e32 v228, s16
	v_and_b32_e32 v229, 32, v178
	v_cmp_ne_u32_e32 vcc, 0, v229
	s_nop 1
	v_cndmask_b32_e32 v183, v228, v183, vcc
	global_load_dwordx4 v[32:35], v183, s[34:35] offset:0
	global_load_dwordx4 v[36:39], v183, s[34:35] offset:16
	global_load_dwordx4 v[40:43], v183, s[34:35] offset:32
	global_load_dwordx4 v[44:47], v183, s[34:35] offset:48
	s_barrier
	global_load_dwordx4 v[120:123], v129, s[4:5]
	global_load_dwordx4 v[124:127], v129, s[4:5] offset:128
	global_load_dwordx4 v[132:135], v130, s[6:7]
	s_add_u32 s4, s4, 0x40000
	s_addc_u32 s5, s5, 0
	s_add_u32 s6, s6, 0x1000
	s_addc_u32 s7, s7, 0
	s_waitcnt vmcnt(0)
	ds_write_b128 v167, v[120:123] offset:0
	ds_write_b128 v131, v[124:127] offset:0
	ds_write_b128 v169, v[132:135] offset:0
	s_waitcnt lgkmcnt(0)
	global_load_dwordx4 v[120:123], v129, s[4:5]
	global_load_dwordx4 v[124:127], v129, s[4:5] offset:128
	global_load_dwordx4 v[132:135], v130, s[6:7]
	s_add_u32 s4, s4, 0x40000
	s_addc_u32 s5, s5, 0
	s_add_u32 s6, s6, 0x1000
	s_addc_u32 s7, s7, 0
	s_waitcnt vmcnt(0)
	ds_write_b128 v167, v[120:123] offset:13312
	ds_write_b128 v131, v[124:127] offset:16384
	ds_write_b128 v169, v[132:135] offset:13312
	s_waitcnt lgkmcnt(0)
; __device__ __forceinline__ unsigned cvtpk(float lo, float hi) { f32x2 v = {lo, hi}; bf16x2_t b = __builtin_convertvector(v, bf16x2_t); return *(unsigned*)&b; }
; __device__ __forceinline__ float lo16(unsigned w) { return __uint_as_float(w << 16); }
; __device__ __forceinline__ float hi16(unsigned w) { return __uint_as_float(w & 0xffff0000u); }
; #define MFMA(a, b, c) __builtin_amdgcn_mfma_f32_32x32x16_bf16((a), (b), (c), 0, 0, 0)
; #define SLOAD(i, k0) do { sr_[i].vs = *(const bf16x8*)(Kh + (size_t)((k0) + skey) * 2048 + 64 + sc8); \
;     sr_[i].ks = *(const bf16x8*)(Kh + (size_t)((k0) + skey) * 2048 + sc8); \
;     sr_[i].ps = *(const bf16x8*)(Kp + (size_t)((k0) + pkey) * 32 + pc8); } while (0)
; __device__ __forceinline__ void at_qkt(f32x16& p0, f32x16& p1, const char* Ks, const bf16x8* qr, int r32, int hi, float negm) {
; #pragma unroll
;   for (int r = 0; r < 16; ++r) { p0[r] = negm; p1[r] = negm; }
; #pragma unroll
;   for (int d0 = 0; d0 < 6; ++d0) {
;     const bf16x8 b0 = *(const bf16x8*)(Ks + r32 * AT_KROW + d0 * 32 + hi * 16);
;     const bf16x8 b1 = *(const bf16x8*)(Ks + (32 + r32) * AT_KROW + d0 * 32 + hi * 16);
;     p0 = MFMA(b0, qr[d0], p0);
;     p1 = MFMA(b1, qr[d0], p1);
;   }
; }
; __device__ void phase_attn(const Params& p, char* lds) {
;     ...
;       const int t = qblk * 256 + wid * 32 + r32;
;       const f32x2* tb = rope + (hi ? (t & 63) : (t >> 6)) * 8;
;       const u32x4 x1 = *(const u32x4*)&qr[4], x2 = *(const u32x4*)&qr[5];
;       u32x4 n1, n2;
; #pragma unroll
;       for (int q = 0; q < 4; ++q) {
;         const f32x2 csA = tb[2 * q], csB = tb[2 * q + 1];
;         const float a0 = lo16(x1[q]), a1 = hi16(x1[q]), b0 = lo16(x2[q]), b1 = hi16(x2[q]);
;         n1[q] = cvtpk(a0 * csA[0] - b0 * csA[1], a1 * csB[0] - b1 * csB[1]);
;         n2[q] = cvtpk(a0 * csA[1] + b0 * csA[0], a1 * csB[1] + b1 * csB[0]);
;       }
;       qr[4] = *(bf16x8*)&n1; qr[5] = *(bf16x8*)&n2;
;     }
;     struct { bf16x8 vs, ks, ps; } sr_[2];
;     ...
;     f32x16 pA0, pA1, pB0, pB1; float alA, alB; bf16x8 pa0, pa1, pa2, pa3;
;     constexpr int NT = TL / 64;
;     SLOAD(0, 0); asm volatile("s_waitcnt vmcnt(0)" ::: "memory"); SWRITE(0, 0); __syncthreads();
;     at_qkt(pA0, pA1, K_lds, qr, r32, hi, 0.f); at_partialSM(pA0, pA1, m_reg, alA, true);
;     SLOAD(1, 64); SLOAD(0, 128);
;     SWAIT(); SWRITE(1, 1); __syncthreads();
	global_load_dwordx4 v[120:123], v129, s[4:5]
	global_load_dwordx4 v[124:127], v129, s[4:5] offset:128
	global_load_dwordx4 v[132:135], v130, s[6:7]
	s_add_u32 s4, s4, 0x40000
	s_addc_u32 s5, s5, 0
	s_add_u32 s6, s6, 0x1000
	s_addc_u32 s7, s7, 0
	v_lshlrev_b32_e32 v175, 16, v96
	v_and_b32_e32 v183, 0xffff0000, v96
	v_lshlrev_b32_e32 v228, 16, v100
	v_and_b32_e32 v229, 0xffff0000, v100
	v_mul_f32_e32 v230, v228, v33
	v_mul_f32_e32 v174, v229, v35
	v_fma_f32 v230, v175, v32, -v230
	v_fma_f32 v174, v183, v34, -v174
	v_mul_f32_e32 v175, v175, v33
	v_mul_f32_e32 v183, v183, v35
	v_fma_f32 v175, v228, v32, v175
	v_fma_f32 v183, v229, v34, v183
	v_cvt_pk_bf16_f32 v96, v230, v174
	v_cvt_pk_bf16_f32 v100, v175, v183
	v_lshlrev_b32_e32 v175, 16, v97
	v_and_b32_e32 v183, 0xffff0000, v97
	v_lshlrev_b32_e32 v228, 16, v101
	v_and_b32_e32 v229, 0xffff0000, v101
	v_mul_f32_e32 v230, v228, v37
	v_mul_f32_e32 v174, v229, v39
	v_fma_f32 v230, v175, v36, -v230
	v_fma_f32 v174, v183, v38, -v174
	v_mul_f32_e32 v175, v175, v37
	v_mul_f32_e32 v183, v183, v39
	v_fma_f32 v175, v228, v36, v175
	v_fma_f32 v183, v229, v38, v183
	v_cvt_pk_bf16_f32 v97, v230, v174
	v_cvt_pk_bf16_f32 v101, v175, v183
	v_lshlrev_b32_e32 v175, 16, v98
	v_and_b32_e32 v183, 0xffff0000, v98
	v_lshlrev_b32_e32 v228, 16, v102
	v_and_b32_e32 v229, 0xffff0000, v102
	v_mul_f32_e32 v230, v228, v41
	v_mul_f32_e32 v174, v229, v43
	v_fma_f32 v230, v175, v40, -v230
	v_fma_f32 v174, v183, v42, -v174
	v_mul_f32_e32 v175, v175, v41
	v_mul_f32_e32 v183, v183, v43
	v_fma_f32 v175, v228, v40, v175
	v_fma_f32 v183, v229, v42, v183
	v_cvt_pk_bf16_f32 v98, v230, v174
	v_cvt_pk_bf16_f32 v102, v175, v183
	v_lshlrev_b32_e32 v175, 16, v99
	v_and_b32_e32 v183, 0xffff0000, v99
	v_lshlrev_b32_e32 v228, 16, v103
	v_and_b32_e32 v229, 0xffff0000, v103
	v_mul_f32_e32 v230, v228, v45
	v_mul_f32_e32 v174, v229, v47
	v_fma_f32 v230, v175, v44, -v230
	v_fma_f32 v174, v183, v46, -v174
	v_mul_f32_e32 v175, v175, v45
	v_mul_f32_e32 v183, v183, v47
	v_fma_f32 v175, v228, v44, v175
	v_fma_f32 v183, v229, v46, v183
	v_cvt_pk_bf16_f32 v99, v230, v174
	v_cvt_pk_bf16_f32 v103, v175, v183
	v_mov_b32_e32 v0, 0
	v_mov_b32_e32 v1, 0
	v_mov_b32_e32 v2, 0
	v_mov_b32_e32 v3, 0
	v_mov_b32_e32 v4, 0
	v_mov_b32_e32 v5, 0
	v_mov_b32_e32 v6, 0
	v_mov_b32_e32 v7, 0
	v_mov_b32_e32 v8, 0
	v_mov_b32_e32 v9, 0
	v_mov_b32_e32 v10, 0
	v_mov_b32_e32 v11, 0
	v_mov_b32_e32 v12, 0
	v_mov_b32_e32 v13, 0
	v_mov_b32_e32 v14, 0
	v_mov_b32_e32 v15, 0
	v_mov_b32_e32 v16, 0
	v_mov_b32_e32 v17, 0
	v_mov_b32_e32 v18, 0
	v_mov_b32_e32 v19, 0
	v_mov_b32_e32 v20, 0
	v_mov_b32_e32 v21, 0
	v_mov_b32_e32 v22, 0
	v_mov_b32_e32 v23, 0
	v_mov_b32_e32 v24, 0
	v_mov_b32_e32 v25, 0
	v_mov_b32_e32 v26, 0
	v_mov_b32_e32 v27, 0
	v_mov_b32_e32 v28, 0
	v_mov_b32_e32 v29, 0
	v_mov_b32_e32 v30, 0
	v_mov_b32_e32 v31, 0
	v_mov_b32_e32 v173, 0
	s_barrier
	ds_read_b128 v[184:187], v170 offset:0
	ds_read_b128 v[188:191], v170 offset:6656
	ds_read_b128 v[192:195], v170 offset:32
	ds_read_b128 v[196:199], v170 offset:6688
	s_cmp_eq_u32 s15, 0
	s_cbranch_scc1 .Lat_nostag
	s_barrier
.Lat_nostag:
	ds_read_b128 v[200:203], v170 offset:64
	ds_read_b128 v[204:207], v170 offset:6720
	s_waitcnt lgkmcnt(5)
	v_mfma_f32_32x32x16_bf16 v[32:47], v[184:187], v[80:83], 0
	s_waitcnt lgkmcnt(4)
	v_mfma_f32_32x32x16_bf16 v[48:63], v[188:191], v[80:83], 0
	ds_read_b128 v[208:211], v170 offset:96
	ds_read_b128 v[212:215], v170 offset:6752
	s_waitcnt lgkmcnt(5)
	v_mfma_f32_32x32x16_bf16 v[32:47], v[192:195], v[84:87], v[32:47]
	s_waitcnt lgkmcnt(4)
	v_mfma_f32_32x32x16_bf16 v[48:63], v[196:199], v[84:87], v[48:63]
	ds_read_b128 v[184:187], v170 offset:128
	ds_read_b128 v[188:191], v170 offset:6784
	s_waitcnt lgkmcnt(5)
	v_mfma_f32_32x32x16_bf16 v[32:47], v[200:203], v[88:91], v[32:47]
	s_waitcnt lgkmcnt(4)
	v_mfma_f32_32x32x16_bf16 v[48:63], v[204:207], v[88:91], v[48:63]
	ds_read_b128 v[192:195], v170 offset:160
	ds_read_b128 v[196:199], v170 offset:6816
	s_waitcnt lgkmcnt(5)
	v_mfma_f32_32x32x16_bf16 v[32:47], v[208:211], v[92:95], v[32:47]
	s_waitcnt lgkmcnt(4)
	v_mfma_f32_32x32x16_bf16 v[48:63], v[212:215], v[92:95], v[48:63]
	s_waitcnt lgkmcnt(3)
	v_mfma_f32_32x32x16_bf16 v[32:47], v[184:187], v[96:99], v[32:47]
	s_waitcnt lgkmcnt(2)
	v_mfma_f32_32x32x16_bf16 v[48:63], v[188:191], v[96:99], v[48:63]
	s_waitcnt lgkmcnt(1)
	v_mfma_f32_32x32x16_bf16 v[32:47], v[192:195], v[100:103], v[32:47]
	s_waitcnt lgkmcnt(0)
	v_mfma_f32_32x32x16_bf16 v[48:63], v[196:199], v[100:103], v[48:63]
	s_nop 11
	v_max3_f32 v174, v32, v33, v34
	v_max3_f32 v175, v48, v49, v50
	v_max3_f32 v174, v174, v35, v36
	v_max3_f32 v175, v175, v51, v52
	v_max3_f32 v174, v174, v37, v38
	v_max3_f32 v175, v175, v53, v54
	v_max3_f32 v174, v174, v39, v40
	v_max3_f32 v175, v175, v55, v56
	v_max3_f32 v174, v174, v41, v42
	v_max3_f32 v175, v175, v57, v58
	v_max3_f32 v174, v174, v43, v44
	v_max3_f32 v175, v175, v59, v60
	v_max3_f32 v174, v174, v45, v46
	v_max3_f32 v175, v175, v61, v62
	v_max3_f32 v174, v174, v47, v63
	v_max_f32_e32 v174, v174, v175
	v_mov_b32_e32 v175, v174
	s_nop 1
	v_permlane32_swap_b32_e32 v174, v175
	v_max_f32_e32 v174, v174, v175
	s_barrier
; __device__ __forceinline__ void at_partialSM(f32x16& p0, f32x16& p1, float& m_reg, float& alpha, bool force) {
;     ...
;   if (__builtin_expect(!force && __all(pm <= AT_THR * 1.4426950408889634f), 1)) { alpha = 1.f; }
;   else {
;     const float dlt = force ? pm : fmaxf(pm, 0.f);
;     alpha = force ? 1.f : __builtin_amdgcn_exp2f(-dlt); m_reg += dlt;
; #pragma unroll
;     for (int r = 0; r < 16; ++r) { p0[r] -= dlt; p1[r] -= dlt; }
;   }
; #pragma unroll
;   for (int r = 0; r < 16; ++r) p0[r] = __builtin_amdgcn_exp2f(p0[r]);
; }
; __device__ __forceinline__ void at_finishSM(f32x16& p0, f32x16& p1, float alpha, float& l_reg, bf16x8& pa0, bf16x8& pa1, bf16x8& pa2, bf16x8& pa3) {
; #pragma unroll
;   for (int r = 0; r < 16; ++r) p1[r] = __builtin_amdgcn_exp2f(p1[r]);
;   float ps = 0;
; #pragma unroll
;   for (int r = 0; r < 16; ++r) ps += p0[r];
; #pragma unroll
;   for (int r = 0; r < 16; ++r) ps += p1[r];
;   { auto rr = __builtin_amdgcn_permlane32_swap(__float_as_uint(ps), __float_as_uint(ps), false, false);
;     ps = __uint_as_float(rr[0]) + __uint_as_float(rr[1]); }
;   l_reg = l_reg * alpha + ps;
;     ...
;   PK4(p0, 0, pa0); PK4(p0, 8, pa1); PK4(p1, 0, pa2); PK4(p1, 8, pa3);
	v_mov_b32_e32 v172, v174
	v_sub_f32_e32 v32, v32, v174
	v_sub_f32_e32 v48, v48, v174
	v_sub_f32_e32 v33, v33, v174
	v_sub_f32_e32 v49, v49, v174
	v_sub_f32_e32 v34, v34, v174
	v_sub_f32_e32 v50, v50, v174
	v_sub_f32_e32 v35, v35, v174
	v_sub_f32_e32 v51, v51, v174
	v_sub_f32_e32 v36, v36, v174
	v_sub_f32_e32 v52, v52, v174
	v_sub_f32_e32 v37, v37, v174
	v_sub_f32_e32 v53, v53, v174
	v_sub_f32_e32 v38, v38, v174
	v_sub_f32_e32 v54, v54, v174
	v_sub_f32_e32 v39, v39, v174
	v_sub_f32_e32 v55, v55, v174
	v_sub_f32_e32 v40, v40, v174
	v_sub_f32_e32 v56, v56, v174
	v_sub_f32_e32 v41, v41, v174
	v_sub_f32_e32 v57, v57, v174
	v_sub_f32_e32 v42, v42, v174
	v_sub_f32_e32 v58, v58, v174
	v_sub_f32_e32 v43, v43, v174
	v_sub_f32_e32 v59, v59, v174
	v_sub_f32_e32 v44, v44, v174
	v_sub_f32_e32 v60, v60, v174
	v_sub_f32_e32 v45, v45, v174
	v_sub_f32_e32 v61, v61, v174
	v_sub_f32_e32 v46, v46, v174
	v_sub_f32_e32 v62, v62, v174
	v_sub_f32_e32 v47, v47, v174
	v_sub_f32_e32 v63, v63, v174
	v_sub_f32_e32 v64, 0, v174
	v_sub_f32_e32 v65, 0, v174
	v_sub_f32_e32 v66, 0, v174
	v_sub_f32_e32 v67, 0, v174
	v_sub_f32_e32 v68, 0, v174
	v_sub_f32_e32 v69, 0, v174
	v_sub_f32_e32 v70, 0, v174
	v_sub_f32_e32 v71, 0, v174
	v_sub_f32_e32 v72, 0, v174
	v_sub_f32_e32 v73, 0, v174
	v_sub_f32_e32 v74, 0, v174
	v_sub_f32_e32 v75, 0, v174
	v_sub_f32_e32 v76, 0, v174
	v_sub_f32_e32 v77, 0, v174
	v_sub_f32_e32 v78, 0, v174
	v_sub_f32_e32 v79, 0, v174
	s_waitcnt vmcnt(0)
	ds_write_b128 v167, v[120:123] offset:26624
	ds_write_b128 v131, v[124:127] offset:32768
	ds_write_b128 v169, v[132:135] offset:26624
	v_exp_f32_e32 v32, v32
	v_exp_f32_e32 v48, v48
	v_exp_f32_e32 v33, v33
	v_exp_f32_e32 v49, v49
	v_exp_f32_e32 v34, v34
	v_exp_f32_e32 v50, v50
	v_exp_f32_e32 v35, v35
	v_exp_f32_e32 v51, v51
	v_exp_f32_e32 v36, v36
	v_exp_f32_e32 v52, v52
	v_exp_f32_e32 v37, v37
	v_exp_f32_e32 v53, v53
	v_exp_f32_e32 v38, v38
	v_exp_f32_e32 v54, v54
	v_exp_f32_e32 v39, v39
	v_exp_f32_e32 v55, v55
	v_exp_f32_e32 v40, v40
	v_exp_f32_e32 v56, v56
	v_exp_f32_e32 v41, v41
	v_exp_f32_e32 v57, v57
	v_exp_f32_e32 v42, v42
	v_exp_f32_e32 v58, v58
	v_exp_f32_e32 v43, v43
	v_exp_f32_e32 v59, v59
	v_exp_f32_e32 v44, v44
	v_exp_f32_e32 v60, v60
	v_exp_f32_e32 v45, v45
	v_exp_f32_e32 v61, v61
	v_exp_f32_e32 v46, v46
	v_exp_f32_e32 v62, v62
	v_exp_f32_e32 v47, v47
	v_exp_f32_e32 v63, v63
	s_waitcnt lgkmcnt(0)
	global_load_dwordx4 v[120:123], v129, s[4:5]
	global_load_dwordx4 v[124:127], v129, s[4:5] offset:128
	global_load_dwordx4 v[132:135], v130, s[6:7]
	s_add_u32 s4, s4, 0x40000
	s_addc_u32 s5, s5, 0
	s_add_u32 s6, s6, 0x1000
	s_addc_u32 s7, s7, 0
	v_add_f32_e32 v175, v32, v33
	v_add_f32_e32 v174, v48, v49
	v_add_f32_e32 v175, v175, v34
	v_add_f32_e32 v174, v174, v50
	v_add_f32_e32 v175, v175, v35
	v_add_f32_e32 v174, v174, v51
	v_add_f32_e32 v175, v175, v36
	v_add_f32_e32 v174, v174, v52
	v_add_f32_e32 v175, v175, v37
	v_add_f32_e32 v174, v174, v53
	v_add_f32_e32 v175, v175, v38
	v_add_f32_e32 v174, v174, v54
	v_add_f32_e32 v175, v175, v39
	v_add_f32_e32 v174, v174, v55
	v_add_f32_e32 v175, v175, v40
	v_add_f32_e32 v174, v174, v56
	v_add_f32_e32 v175, v175, v41
	v_add_f32_e32 v174, v174, v57
	v_add_f32_e32 v175, v175, v42
	v_add_f32_e32 v174, v174, v58
	v_add_f32_e32 v175, v175, v43
	v_add_f32_e32 v174, v174, v59
	v_add_f32_e32 v175, v175, v44
	v_add_f32_e32 v174, v174, v60
	v_add_f32_e32 v175, v175, v45
	v_add_f32_e32 v174, v174, v61
	v_add_f32_e32 v175, v175, v46
	v_add_f32_e32 v174, v174, v62
	v_add_f32_e32 v175, v175, v47
	v_add_f32_e32 v174, v174, v63
	v_add_f32_e32 v175, v175, v174
	v_add_f32_e32 v173, v173, v175
	v_cvt_pk_bf16_f32 v104, v32, v33
	v_cvt_pk_bf16_f32 v105, v34, v35
	v_cvt_pk_bf16_f32 v106, v36, v37
	v_cvt_pk_bf16_f32 v107, v38, v39
	v_cvt_pk_bf16_f32 v108, v40, v41
	v_cvt_pk_bf16_f32 v109, v42, v43
	v_cvt_pk_bf16_f32 v110, v44, v45
	v_cvt_pk_bf16_f32 v111, v46, v47
	v_cvt_pk_bf16_f32 v112, v48, v49
	v_cvt_pk_bf16_f32 v113, v50, v51
	v_cvt_pk_bf16_f32 v114, v52, v53
	v_cvt_pk_bf16_f32 v115, v54, v55
	v_cvt_pk_bf16_f32 v116, v56, v57
	v_cvt_pk_bf16_f32 v117, v58, v59
	v_cvt_pk_bf16_f32 v118, v60, v61
	v_cvt_pk_bf16_f32 v119, v62, v63
	ds_read_b128 v[184:187], v170 offset:13312
	ds_read_b128 v[188:191], v170 offset:19968
	ds_read_b128 v[192:195], v170 offset:13344
	ds_read_b128 v[196:199], v170 offset:20000
	s_barrier
	s_mov_b32 s13, 32
; __device__ __forceinline__ void at_partialSM(f32x16& p0, f32x16& p1, float& m_reg, float& alpha, bool force) {
;   float pm = p0[0];
; #pragma unroll
;   for (int r = 1; r < 16; ++r) pm = fmaxf(pm, p0[r]);
; #pragma unroll
;   for (int r = 0; r < 16; ++r) pm = fmaxf(pm, p1[r]);
;   { auto rr = __builtin_amdgcn_permlane32_swap(__float_as_uint(pm), __float_as_uint(pm), false, false);
;     pm = fmaxf(__uint_as_float(rr[0]), __uint_as_float(rr[1])); }
;   if (__builtin_expect(!force && __all(pm <= AT_THR * 1.4426950408889634f), 1)) { alpha = 1.f; }
;   else {
;     const float dlt = force ? pm : fmaxf(pm, 0.f);
;     alpha = force ? 1.f : __builtin_amdgcn_exp2f(-dlt); m_reg += dlt;
; #pragma unroll
;     for (int r = 0; r < 16; ++r) { p0[r] -= dlt; p1[r] -= dlt; }
;   }
; #pragma unroll
;   for (int r = 0; r < 16; ++r) p0[r] = __builtin_amdgcn_exp2f(p0[r]);
; }
; __device__ __forceinline__ void at_finishSM(f32x16& p0, f32x16& p1, float alpha, float& l_reg, bf16x8& pa0, bf16x8& pa1, bf16x8& pa2, bf16x8& pa3) {
; #pragma unroll
;   for (int r = 0; r < 16; ++r) p1[r] = __builtin_amdgcn_exp2f(p1[r]);
;   float ps = 0;
; #pragma unroll
;   for (int r = 0; r < 16; ++r) ps += p0[r];
; #pragma unroll
;   for (int r = 0; r < 16; ++r) ps += p1[r];
;   { auto rr = __builtin_amdgcn_permlane32_swap(__float_as_uint(ps), __float_as_uint(ps), false, false);
;     ps = __uint_as_float(rr[0]) + __uint_as_float(rr[1]); }
;   l_reg = l_reg * alpha + ps;
;     ...
;   PK4(p0, 0, pa0); PK4(p0, 8, pa1); PK4(p1, 0, pa2); PK4(p1, 8, pa3);
; __device__ void phase_attn(const Params& p, char* lds) {
;     ...
;     for (int j = 1; j + 1 < NT; j += 2) {
;       SBAR(); at_qkt(pB0, pB1, K_lds + AT_SHMK, qr, r32, hi, -m_reg);
;       at_finishSM(pA0, pA1, alA, l_reg, pa0, pa1, pa2, pa3); SBAR();
;       SLOAD(1, (j + 2) * 64); SBAR();
;       pv_d0(o, vb0, pa0, pa1, pa2, pa3); at_partialSM(pB0, pB1, m_reg, alB, false);
;       __syncthreads(); SWAIT(); SWRITE(0, 0);
;       RESC(alB); __syncthreads();
;       SBAR(); at_qkt(pA0, pA1, K_lds, qr, r32, hi, -m_reg);
;       at_finishSM(pB0, pB1, alB, l_reg, pa0, pa1, pa2, pa3); SBAR();
;       if (j + 3 < NT) SLOAD(0, (j + 3) * 64); SBAR();
;       pv_d0(o, vb0 + AT_SHMV, pa0, pa1, pa2, pa3); at_partialSM(pA0, pA1, m_reg, alA, false);
;       __syncthreads(); SWAIT(); SWRITE(1, 1);
;       RESC(alA); __syncthreads();
;     }
.Lat_loop:
	ds_read_b128 v[200:203], v170 offset:13376
	ds_read_b128 v[204:207], v170 offset:20032
	s_waitcnt lgkmcnt(5)
	v_mfma_f32_32x32x16_bf16 v[32:47], v[184:187], v[80:83], v[64:79]
	s_waitcnt lgkmcnt(4)
	v_mfma_f32_32x32x16_bf16 v[48:63], v[188:191], v[80:83], v[64:79]
	ds_read_b128 v[208:211], v170 offset:13408
	ds_read_b128 v[212:215], v170 offset:20064
	s_waitcnt lgkmcnt(5)
	v_mfma_f32_32x32x16_bf16 v[32:47], v[192:195], v[84:87], v[32:47]
	s_waitcnt lgkmcnt(4)
	v_mfma_f32_32x32x16_bf16 v[48:63], v[196:199], v[84:87], v[48:63]
	ds_read_b128 v[184:187], v170 offset:13440
	ds_read_b128 v[188:191], v170 offset:20096
	s_waitcnt lgkmcnt(5)
	v_mfma_f32_32x32x16_bf16 v[32:47], v[200:203], v[88:91], v[32:47]
	s_waitcnt lgkmcnt(4)
	v_mfma_f32_32x32x16_bf16 v[48:63], v[204:207], v[88:91], v[48:63]
	ds_read_b128 v[192:195], v170 offset:13472
	ds_read_b128 v[196:199], v170 offset:20128
	s_waitcnt lgkmcnt(5)
	v_mfma_f32_32x32x16_bf16 v[32:47], v[208:211], v[92:95], v[32:47]
	s_waitcnt lgkmcnt(4)
	v_mfma_f32_32x32x16_bf16 v[48:63], v[212:215], v[92:95], v[48:63]
	ds_read_b64_tr_b16 v[148:149], v171 offset:0
	ds_read_b64_tr_b16 v[150:151], v171 offset:2048
	ds_read_b64_tr_b16 v[152:153], v171 offset:4096
	ds_read_b64_tr_b16 v[154:155], v171 offset:6144
	s_waitcnt lgkmcnt(7)
	v_mfma_f32_32x32x16_bf16 v[32:47], v[184:187], v[96:99], v[32:47]
	s_waitcnt lgkmcnt(6)
	v_mfma_f32_32x32x16_bf16 v[48:63], v[188:191], v[96:99], v[48:63]
	ds_read_b64_tr_b16 v[156:157], v171 offset:8192
	ds_read_b64_tr_b16 v[158:159], v171 offset:10240
	ds_read_b64_tr_b16 v[216:217], v171 offset:12288
	ds_read_b64_tr_b16 v[218:219], v171 offset:14336
	s_waitcnt lgkmcnt(9)
	v_mfma_f32_32x32x16_bf16 v[32:47], v[192:195], v[100:103], v[32:47]
	s_waitcnt lgkmcnt(8)
	v_mfma_f32_32x32x16_bf16 v[48:63], v[196:199], v[100:103], v[48:63]
	ds_read_b64_tr_b16 v[220:221], v171 offset:512
	ds_read_b64_tr_b16 v[222:223], v171 offset:2560
	ds_read_b64_tr_b16 v[224:225], v171 offset:4608
	ds_read_b64_tr_b16 v[226:227], v171 offset:6656
	s_waitcnt lgkmcnt(10)
	v_mfma_f32_32x32x16_bf16 v[0:15], v[104:107], v[148:151], v[0:15]
	s_waitcnt lgkmcnt(8)
	v_mfma_f32_32x32x16_bf16 v[0:15], v[108:111], v[152:155], v[0:15]
	ds_read_b64_tr_b16 v[236:237], v171 offset:8704
	ds_read_b64_tr_b16 v[238:239], v171 offset:10752
	ds_read_b64_tr_b16 v[240:241], v171 offset:12800
	ds_read_b64_tr_b16 v[242:243], v171 offset:14848
	s_waitcnt lgkmcnt(10)
	v_mfma_f32_32x32x16_bf16 v[0:15], v[112:115], v[156:159], v[0:15]
	s_waitcnt lgkmcnt(8)
	v_mfma_f32_32x32x16_bf16 v[0:15], v[116:119], v[216:219], v[0:15]
	s_waitcnt lgkmcnt(6)
	v_mfma_f32_32x32x16_bf16 v[16:31], v[104:107], v[220:223], v[16:31]
	v_max3_f32 v174, v32, v33, v34
	v_max3_f32 v175, v48, v49, v50
	v_max3_f32 v174, v174, v35, v36
	v_max3_f32 v175, v175, v51, v52
	v_max3_f32 v174, v174, v37, v38
	v_max3_f32 v175, v175, v53, v54
	s_waitcnt lgkmcnt(4)
	v_mfma_f32_32x32x16_bf16 v[16:31], v[108:111], v[224:227], v[16:31]
	v_max3_f32 v174, v174, v39, v40
	v_max3_f32 v175, v175, v55, v56
	v_max3_f32 v174, v174, v41, v42
	v_max3_f32 v175, v175, v57, v58
	v_max3_f32 v174, v174, v43, v44
	v_max3_f32 v175, v175, v59, v60
	s_waitcnt lgkmcnt(2)
	v_mfma_f32_32x32x16_bf16 v[16:31], v[112:115], v[236:239], v[16:31]
	v_max3_f32 v174, v174, v45, v46
	v_max3_f32 v175, v175, v61, v62
	v_max3_f32 v174, v174, v47, v63
	v_max_f32_e32 v174, v174, v175
	s_waitcnt lgkmcnt(0)
	v_mfma_f32_32x32x16_bf16 v[16:31], v[116:119], v[240:243], v[16:31]
	v_mov_b32_e32 v175, v174
	s_nop 1
	v_permlane32_swap_b32_e32 v174, v175
	v_max_f32_e32 v174, v174, v175
	v_cmp_ge_f32_e32 vcc, s23, v174
	s_cmp_eq_u64 vcc, exec
	s_barrier
	s_cbranch_scc0 .Lat_rare0
.Lat_rare0_back:
	s_waitcnt vmcnt(0)
	ds_write_b128 v167, v[120:123] offset:39936
	ds_write_b128 v131, v[124:127] offset:49152
	ds_write_b128 v169, v[132:135] offset:39936
	v_exp_f32_e32 v32, v32
	v_exp_f32_e32 v48, v48
	v_exp_f32_e32 v33, v33
	v_exp_f32_e32 v49, v49
	v_exp_f32_e32 v34, v34
	v_exp_f32_e32 v50, v50
	v_exp_f32_e32 v35, v35
	v_exp_f32_e32 v51, v51
	v_exp_f32_e32 v36, v36
	v_exp_f32_e32 v52, v52
	v_exp_f32_e32 v37, v37
	v_exp_f32_e32 v53, v53
	v_exp_f32_e32 v38, v38
	v_exp_f32_e32 v54, v54
	v_exp_f32_e32 v39, v39
	v_exp_f32_e32 v55, v55
	v_exp_f32_e32 v40, v40
	v_exp_f32_e32 v56, v56
	v_exp_f32_e32 v41, v41
	v_exp_f32_e32 v57, v57
	v_exp_f32_e32 v42, v42
	v_exp_f32_e32 v58, v58
	v_exp_f32_e32 v43, v43
	v_exp_f32_e32 v59, v59
	v_exp_f32_e32 v44, v44
	v_exp_f32_e32 v60, v60
	v_exp_f32_e32 v45, v45
	v_exp_f32_e32 v61, v61
	v_exp_f32_e32 v46, v46
	v_exp_f32_e32 v62, v62
	v_exp_f32_e32 v47, v47
	v_exp_f32_e32 v63, v63
	s_waitcnt lgkmcnt(0)
	global_load_dwordx4 v[120:123], v129, s[4:5]
	global_load_dwordx4 v[124:127], v129, s[4:5] offset:128
	global_load_dwordx4 v[132:135], v130, s[6:7]
	s_add_u32 s4, s4, 0x40000
	s_addc_u32 s5, s5, 0
	s_add_u32 s6, s6, 0x1000
	s_addc_u32 s7, s7, 0
	v_add_f32_e32 v175, v32, v33
	v_add_f32_e32 v174, v48, v49
	v_add_f32_e32 v175, v175, v34
	v_add_f32_e32 v174, v174, v50
	v_add_f32_e32 v175, v175, v35
	v_add_f32_e32 v174, v174, v51
	v_add_f32_e32 v175, v175, v36
	v_add_f32_e32 v174, v174, v52
	v_add_f32_e32 v175, v175, v37
	v_add_f32_e32 v174, v174, v53
	v_add_f32_e32 v175, v175, v38
	v_add_f32_e32 v174, v174, v54
	v_add_f32_e32 v175, v175, v39
	v_add_f32_e32 v174, v174, v55
	v_add_f32_e32 v175, v175, v40
	v_add_f32_e32 v174, v174, v56
	v_add_f32_e32 v175, v175, v41
	v_add_f32_e32 v174, v174, v57
	v_add_f32_e32 v175, v175, v42
	v_add_f32_e32 v174, v174, v58
	v_add_f32_e32 v175, v175, v43
	v_add_f32_e32 v174, v174, v59
	v_add_f32_e32 v175, v175, v44
	v_add_f32_e32 v174, v174, v60
	v_add_f32_e32 v175, v175, v45
	v_add_f32_e32 v174, v174, v61
	v_add_f32_e32 v175, v175, v46
	v_add_f32_e32 v174, v174, v62
	v_add_f32_e32 v175, v175, v47
	v_add_f32_e32 v174, v174, v63
	v_add_f32_e32 v175, v175, v174
	v_add_f32_e32 v173, v173, v175
	v_cvt_pk_bf16_f32 v104, v32, v33
	v_cvt_pk_bf16_f32 v105, v34, v35
	v_cvt_pk_bf16_f32 v106, v36, v37
	v_cvt_pk_bf16_f32 v107, v38, v39
	v_cvt_pk_bf16_f32 v108, v40, v41
	v_cvt_pk_bf16_f32 v109, v42, v43
	v_cvt_pk_bf16_f32 v110, v44, v45
	v_cvt_pk_bf16_f32 v111, v46, v47
	v_cvt_pk_bf16_f32 v112, v48, v49
	v_cvt_pk_bf16_f32 v113, v50, v51
	v_cvt_pk_bf16_f32 v114, v52, v53
	v_cvt_pk_bf16_f32 v115, v54, v55
	v_cvt_pk_bf16_f32 v116, v56, v57
	v_cvt_pk_bf16_f32 v117, v58, v59
	v_cvt_pk_bf16_f32 v118, v60, v61
	v_cvt_pk_bf16_f32 v119, v62, v63
	ds_read_b128 v[184:187], v170 offset:26624
	ds_read_b128 v[188:191], v170 offset:33280
	ds_read_b128 v[192:195], v170 offset:26656
	ds_read_b128 v[196:199], v170 offset:33312
	s_barrier
; __device__ __forceinline__ void at_partialSM(f32x16& p0, f32x16& p1, float& m_reg, float& alpha, bool force) {
;   float pm = p0[0];
; #pragma unroll
;   for (int r = 1; r < 16; ++r) pm = fmaxf(pm, p0[r]);
; #pragma unroll
;   for (int r = 0; r < 16; ++r) pm = fmaxf(pm, p1[r]);
;   { auto rr = __builtin_amdgcn_permlane32_swap(__float_as_uint(pm), __float_as_uint(pm), false, false);
;     pm = fmaxf(__uint_as_float(rr[0]), __uint_as_float(rr[1])); }
;   if (__builtin_expect(!force && __all(pm <= AT_THR * 1.4426950408889634f), 1)) { alpha = 1.f; }
;   else {
;     const float dlt = force ? pm : fmaxf(pm, 0.f);
;     alpha = force ? 1.f : __builtin_amdgcn_exp2f(-dlt); m_reg += dlt;
; #pragma unroll
;     for (int r = 0; r < 16; ++r) { p0[r] -= dlt; p1[r] -= dlt; }
;   }
; #pragma unroll
;   for (int r = 0; r < 16; ++r) p0[r] = __builtin_amdgcn_exp2f(p0[r]);
; }
; __device__ __forceinline__ void at_finishSM(f32x16& p0, f32x16& p1, float alpha, float& l_reg, bf16x8& pa0, bf16x8& pa1, bf16x8& pa2, bf16x8& pa3) {
; #pragma unroll
;   for (int r = 0; r < 16; ++r) p1[r] = __builtin_amdgcn_exp2f(p1[r]);
;   float ps = 0;
; #pragma unroll
;   for (int r = 0; r < 16; ++r) ps += p0[r];
; #pragma unroll
;   for (int r = 0; r < 16; ++r) ps += p1[r];
;   { auto rr = __builtin_amdgcn_permlane32_swap(__float_as_uint(ps), __float_as_uint(ps), false, false);
;     ps = __uint_as_float(rr[0]) + __uint_as_float(rr[1]); }
;   l_reg = l_reg * alpha + ps;
;     ...
;   PK4(p0, 0, pa0); PK4(p0, 8, pa1); PK4(p1, 0, pa2); PK4(p1, 8, pa3);
; __device__ void phase_attn(const Params& p, char* lds) {
;     ...
;     for (int j = 1; j + 1 < NT; j += 2) {
;       SBAR(); at_qkt(pB0, pB1, K_lds + AT_SHMK, qr, r32, hi, -m_reg);
;       at_finishSM(pA0, pA1, alA, l_reg, pa0, pa1, pa2, pa3); SBAR();
;       SLOAD(1, (j + 2) * 64); SBAR();
;       pv_d0(o, vb0, pa0, pa1, pa2, pa3); at_partialSM(pB0, pB1, m_reg, alB, false);
;       __syncthreads(); SWAIT(); SWRITE(0, 0);
;       RESC(alB); __syncthreads();
;       SBAR(); at_qkt(pA0, pA1, K_lds, qr, r32, hi, -m_reg);
;       at_finishSM(pB0, pB1, alB, l_reg, pa0, pa1, pa2, pa3); SBAR();
;       if (j + 3 < NT) SLOAD(0, (j + 3) * 64); SBAR();
;       pv_d0(o, vb0 + AT_SHMV, pa0, pa1, pa2, pa3); at_partialSM(pA0, pA1, m_reg, alA, false);
;       __syncthreads(); SWAIT(); SWRITE(1, 1);
;       RESC(alA); __syncthreads();
;     }
	ds_read_b128 v[200:203], v170 offset:26688
	ds_read_b128 v[204:207], v170 offset:33344
	s_waitcnt lgkmcnt(5)
	v_mfma_f32_32x32x16_bf16 v[32:47], v[184:187], v[80:83], v[64:79]
	s_waitcnt lgkmcnt(4)
	v_mfma_f32_32x32x16_bf16 v[48:63], v[188:191], v[80:83], v[64:79]
	ds_read_b128 v[208:211], v170 offset:26720
	ds_read_b128 v[212:215], v170 offset:33376
	s_waitcnt lgkmcnt(5)
	v_mfma_f32_32x32x16_bf16 v[32:47], v[192:195], v[84:87], v[32:47]
	s_waitcnt lgkmcnt(4)
	v_mfma_f32_32x32x16_bf16 v[48:63], v[196:199], v[84:87], v[48:63]
	ds_read_b128 v[184:187], v170 offset:26752
	ds_read_b128 v[188:191], v170 offset:33408
	s_waitcnt lgkmcnt(5)
	v_mfma_f32_32x32x16_bf16 v[32:47], v[200:203], v[88:91], v[32:47]
	s_waitcnt lgkmcnt(4)
	v_mfma_f32_32x32x16_bf16 v[48:63], v[204:207], v[88:91], v[48:63]
	ds_read_b128 v[192:195], v170 offset:26784
	ds_read_b128 v[196:199], v170 offset:33440
	s_waitcnt lgkmcnt(5)
	v_mfma_f32_32x32x16_bf16 v[32:47], v[208:211], v[92:95], v[32:47]
	s_waitcnt lgkmcnt(4)
	v_mfma_f32_32x32x16_bf16 v[48:63], v[212:215], v[92:95], v[48:63]
	ds_read_b64_tr_b16 v[148:149], v171 offset:16384
	ds_read_b64_tr_b16 v[150:151], v171 offset:18432
	ds_read_b64_tr_b16 v[152:153], v171 offset:20480
	ds_read_b64_tr_b16 v[154:155], v171 offset:22528
	s_waitcnt lgkmcnt(7)
	v_mfma_f32_32x32x16_bf16 v[32:47], v[184:187], v[96:99], v[32:47]
	s_waitcnt lgkmcnt(6)
	v_mfma_f32_32x32x16_bf16 v[48:63], v[188:191], v[96:99], v[48:63]
	ds_read_b64_tr_b16 v[156:157], v171 offset:24576
	ds_read_b64_tr_b16 v[158:159], v171 offset:26624
	ds_read_b64_tr_b16 v[216:217], v171 offset:28672
	ds_read_b64_tr_b16 v[218:219], v171 offset:30720
	s_waitcnt lgkmcnt(9)
	v_mfma_f32_32x32x16_bf16 v[32:47], v[192:195], v[100:103], v[32:47]
	s_waitcnt lgkmcnt(8)
	v_mfma_f32_32x32x16_bf16 v[48:63], v[196:199], v[100:103], v[48:63]
	ds_read_b64_tr_b16 v[220:221], v171 offset:16896
	ds_read_b64_tr_b16 v[222:223], v171 offset:18944
	ds_read_b64_tr_b16 v[224:225], v171 offset:20992
	ds_read_b64_tr_b16 v[226:227], v171 offset:23040
	s_waitcnt lgkmcnt(10)
	v_mfma_f32_32x32x16_bf16 v[0:15], v[104:107], v[148:151], v[0:15]
	s_waitcnt lgkmcnt(8)
	v_mfma_f32_32x32x16_bf16 v[0:15], v[108:111], v[152:155], v[0:15]
	ds_read_b64_tr_b16 v[236:237], v171 offset:25088
	ds_read_b64_tr_b16 v[238:239], v171 offset:27136
	ds_read_b64_tr_b16 v[240:241], v171 offset:29184
	ds_read_b64_tr_b16 v[242:243], v171 offset:31232
	s_waitcnt lgkmcnt(10)
	v_mfma_f32_32x32x16_bf16 v[0:15], v[112:115], v[156:159], v[0:15]
	s_waitcnt lgkmcnt(8)
	v_mfma_f32_32x32x16_bf16 v[0:15], v[116:119], v[216:219], v[0:15]
	s_waitcnt lgkmcnt(6)
	v_mfma_f32_32x32x16_bf16 v[16:31], v[104:107], v[220:223], v[16:31]
	v_max3_f32 v174, v32, v33, v34
	v_max3_f32 v175, v48, v49, v50
	v_max3_f32 v174, v174, v35, v36
	v_max3_f32 v175, v175, v51, v52
	v_max3_f32 v174, v174, v37, v38
	v_max3_f32 v175, v175, v53, v54
	s_waitcnt lgkmcnt(4)
	v_mfma_f32_32x32x16_bf16 v[16:31], v[108:111], v[224:227], v[16:31]
	v_max3_f32 v174, v174, v39, v40
	v_max3_f32 v175, v175, v55, v56
	v_max3_f32 v174, v174, v41, v42
	v_max3_f32 v175, v175, v57, v58
	v_max3_f32 v174, v174, v43, v44
	v_max3_f32 v175, v175, v59, v60
	s_waitcnt lgkmcnt(2)
	v_mfma_f32_32x32x16_bf16 v[16:31], v[112:115], v[236:239], v[16:31]
	v_max3_f32 v174, v174, v45, v46
	v_max3_f32 v175, v175, v61, v62
	v_max3_f32 v174, v174, v47, v63
	v_max_f32_e32 v174, v174, v175
	s_waitcnt lgkmcnt(0)
	v_mfma_f32_32x32x16_bf16 v[16:31], v[116:119], v[240:243], v[16:31]
	v_mov_b32_e32 v175, v174
	s_nop 1
	v_permlane32_swap_b32_e32 v174, v175
	v_max_f32_e32 v174, v174, v175
	v_cmp_ge_f32_e32 vcc, s23, v174
	s_cmp_eq_u64 vcc, exec
	s_barrier
	s_cbranch_scc0 .Lat_rare1
.Lat_rare1_back:
	s_waitcnt vmcnt(0)
	ds_write_b128 v167, v[120:123] offset:0
	ds_write_b128 v131, v[124:127] offset:0
	ds_write_b128 v169, v[132:135] offset:0
	v_exp_f32_e32 v32, v32
	v_exp_f32_e32 v48, v48
	v_exp_f32_e32 v33, v33
	v_exp_f32_e32 v49, v49
	v_exp_f32_e32 v34, v34
	v_exp_f32_e32 v50, v50
	v_exp_f32_e32 v35, v35
	v_exp_f32_e32 v51, v51
	v_exp_f32_e32 v36, v36
	v_exp_f32_e32 v52, v52
	v_exp_f32_e32 v37, v37
	v_exp_f32_e32 v53, v53
	v_exp_f32_e32 v38, v38
	v_exp_f32_e32 v54, v54
	v_exp_f32_e32 v39, v39
	v_exp_f32_e32 v55, v55
	v_exp_f32_e32 v40, v40
	v_exp_f32_e32 v56, v56
	v_exp_f32_e32 v41, v41
	v_exp_f32_e32 v57, v57
	v_exp_f32_e32 v42, v42
	v_exp_f32_e32 v58, v58
	v_exp_f32_e32 v43, v43
	v_exp_f32_e32 v59, v59
	v_exp_f32_e32 v44, v44
	v_exp_f32_e32 v60, v60
	v_exp_f32_e32 v45, v45
	v_exp_f32_e32 v61, v61
	v_exp_f32_e32 v46, v46
	v_exp_f32_e32 v62, v62
	v_exp_f32_e32 v47, v47
	v_exp_f32_e32 v63, v63
	s_waitcnt lgkmcnt(0)
	global_load_dwordx4 v[120:123], v129, s[4:5]
	global_load_dwordx4 v[124:127], v129, s[4:5] offset:128
	global_load_dwordx4 v[132:135], v130, s[6:7]
	s_add_u32 s4, s4, 0x40000
	s_addc_u32 s5, s5, 0
	s_add_u32 s6, s6, 0x1000
	s_addc_u32 s7, s7, 0
	v_add_f32_e32 v175, v32, v33
	v_add_f32_e32 v174, v48, v49
	v_add_f32_e32 v175, v175, v34
	v_add_f32_e32 v174, v174, v50
	v_add_f32_e32 v175, v175, v35
	v_add_f32_e32 v174, v174, v51
	v_add_f32_e32 v175, v175, v36
	v_add_f32_e32 v174, v174, v52
	v_add_f32_e32 v175, v175, v37
	v_add_f32_e32 v174, v174, v53
	v_add_f32_e32 v175, v175, v38
	v_add_f32_e32 v174, v174, v54
	v_add_f32_e32 v175, v175, v39
	v_add_f32_e32 v174, v174, v55
	v_add_f32_e32 v175, v175, v40
	v_add_f32_e32 v174, v174, v56
	v_add_f32_e32 v175, v175, v41
	v_add_f32_e32 v174, v174, v57
	v_add_f32_e32 v175, v175, v42
	v_add_f32_e32 v174, v174, v58
	v_add_f32_e32 v175, v175, v43
	v_add_f32_e32 v174, v174, v59
	v_add_f32_e32 v175, v175, v44
	v_add_f32_e32 v174, v174, v60
	v_add_f32_e32 v175, v175, v45
	v_add_f32_e32 v174, v174, v61
	v_add_f32_e32 v175, v175, v46
	v_add_f32_e32 v174, v174, v62
	v_add_f32_e32 v175, v175, v47
	v_add_f32_e32 v174, v174, v63
	v_add_f32_e32 v175, v175, v174
	v_add_f32_e32 v173, v173, v175
	v_cvt_pk_bf16_f32 v104, v32, v33
	v_cvt_pk_bf16_f32 v105, v34, v35
	v_cvt_pk_bf16_f32 v106, v36, v37
	v_cvt_pk_bf16_f32 v107, v38, v39
	v_cvt_pk_bf16_f32 v108, v40, v41
	v_cvt_pk_bf16_f32 v109, v42, v43
	v_cvt_pk_bf16_f32 v110, v44, v45
	v_cvt_pk_bf16_f32 v111, v46, v47
	v_cvt_pk_bf16_f32 v112, v48, v49
	v_cvt_pk_bf16_f32 v113, v50, v51
	v_cvt_pk_bf16_f32 v114, v52, v53
	v_cvt_pk_bf16_f32 v115, v54, v55
	v_cvt_pk_bf16_f32 v116, v56, v57
	v_cvt_pk_bf16_f32 v117, v58, v59
	v_cvt_pk_bf16_f32 v118, v60, v61
	v_cvt_pk_bf16_f32 v119, v62, v63
	ds_read_b128 v[184:187], v170 offset:39936
	ds_read_b128 v[188:191], v170 offset:46592
	ds_read_b128 v[192:195], v170 offset:39968
	ds_read_b128 v[196:199], v170 offset:46624
	s_barrier
; __device__ __forceinline__ void at_partialSM(f32x16& p0, f32x16& p1, float& m_reg, float& alpha, bool force) {
;   float pm = p0[0];
; #pragma unroll
;   for (int r = 1; r < 16; ++r) pm = fmaxf(pm, p0[r]);
; #pragma unroll
;   for (int r = 0; r < 16; ++r) pm = fmaxf(pm, p1[r]);
;   { auto rr = __builtin_amdgcn_permlane32_swap(__float_as_uint(pm), __float_as_uint(pm), false, false);
;     pm = fmaxf(__uint_as_float(rr[0]), __uint_as_float(rr[1])); }
;   if (__builtin_expect(!force && __all(pm <= AT_THR * 1.4426950408889634f), 1)) { alpha = 1.f; }
;   else {
;     const float dlt = force ? pm : fmaxf(pm, 0.f);
;     alpha = force ? 1.f : __builtin_amdgcn_exp2f(-dlt); m_reg += dlt;
; #pragma unroll
;     for (int r = 0; r < 16; ++r) { p0[r] -= dlt; p1[r] -= dlt; }
;   }
; #pragma unroll
;   for (int r = 0; r < 16; ++r) p0[r] = __builtin_amdgcn_exp2f(p0[r]);
; }
; __device__ __forceinline__ void at_finishSM(f32x16& p0, f32x16& p1, float alpha, float& l_reg, bf16x8& pa0, bf16x8& pa1, bf16x8& pa2, bf16x8& pa3) {
; #pragma unroll
;   for (int r = 0; r < 16; ++r) p1[r] = __builtin_amdgcn_exp2f(p1[r]);
;   float ps = 0;
; #pragma unroll
;   for (int r = 0; r < 16; ++r) ps += p0[r];
; #pragma unroll
;   for (int r = 0; r < 16; ++r) ps += p1[r];
;   { auto rr = __builtin_amdgcn_permlane32_swap(__float_as_uint(ps), __float_as_uint(ps), false, false);
;     ps = __uint_as_float(rr[0]) + __uint_as_float(rr[1]); }
;   l_reg = l_reg * alpha + ps;
;     ...
;   PK4(p0, 0, pa0); PK4(p0, 8, pa1); PK4(p1, 0, pa2); PK4(p1, 8, pa3);
; __device__ void phase_attn(const Params& p, char* lds) {
;     ...
;     for (int j = 1; j + 1 < NT; j += 2) {
;       SBAR(); at_qkt(pB0, pB1, K_lds + AT_SHMK, qr, r32, hi, -m_reg);
;       at_finishSM(pA0, pA1, alA, l_reg, pa0, pa1, pa2, pa3); SBAR();
;       SLOAD(1, (j + 2) * 64); SBAR();
;       pv_d0(o, vb0, pa0, pa1, pa2, pa3); at_partialSM(pB0, pB1, m_reg, alB, false);
;       __syncthreads(); SWAIT(); SWRITE(0, 0);
;       RESC(alB); __syncthreads();
;       SBAR(); at_qkt(pA0, pA1, K_lds, qr, r32, hi, -m_reg);
;       at_finishSM(pB0, pB1, alB, l_reg, pa0, pa1, pa2, pa3); SBAR();
;       if (j + 3 < NT) SLOAD(0, (j + 3) * 64); SBAR();
;       pv_d0(o, vb0 + AT_SHMV, pa0, pa1, pa2, pa3); at_partialSM(pA0, pA1, m_reg, alA, false);
;       __syncthreads(); SWAIT(); SWRITE(1, 1);
;       RESC(alA); __syncthreads();
;     }
	ds_read_b128 v[200:203], v170 offset:40000
	ds_read_b128 v[204:207], v170 offset:46656
	s_waitcnt lgkmcnt(5)
	v_mfma_f32_32x32x16_bf16 v[32:47], v[184:187], v[80:83], v[64:79]
	s_waitcnt lgkmcnt(4)
	v_mfma_f32_32x32x16_bf16 v[48:63], v[188:191], v[80:83], v[64:79]
	ds_read_b128 v[208:211], v170 offset:40032
	ds_read_b128 v[212:215], v170 offset:46688
	s_waitcnt lgkmcnt(5)
	v_mfma_f32_32x32x16_bf16 v[32:47], v[192:195], v[84:87], v[32:47]
	s_waitcnt lgkmcnt(4)
	v_mfma_f32_32x32x16_bf16 v[48:63], v[196:199], v[84:87], v[48:63]
	ds_read_b128 v[184:187], v170 offset:40064
	ds_read_b128 v[188:191], v170 offset:46720
	s_waitcnt lgkmcnt(5)
	v_mfma_f32_32x32x16_bf16 v[32:47], v[200:203], v[88:91], v[32:47]
	s_waitcnt lgkmcnt(4)
	v_mfma_f32_32x32x16_bf16 v[48:63], v[204:207], v[88:91], v[48:63]
	ds_read_b128 v[192:195], v170 offset:40096
	ds_read_b128 v[196:199], v170 offset:46752
	s_waitcnt lgkmcnt(5)
	v_mfma_f32_32x32x16_bf16 v[32:47], v[208:211], v[92:95], v[32:47]
	s_waitcnt lgkmcnt(4)
	v_mfma_f32_32x32x16_bf16 v[48:63], v[212:215], v[92:95], v[48:63]
	ds_read_b64_tr_b16 v[148:149], v171 offset:32768
	ds_read_b64_tr_b16 v[150:151], v171 offset:34816
	ds_read_b64_tr_b16 v[152:153], v171 offset:36864
	ds_read_b64_tr_b16 v[154:155], v171 offset:38912
	s_waitcnt lgkmcnt(7)
	v_mfma_f32_32x32x16_bf16 v[32:47], v[184:187], v[96:99], v[32:47]
	s_waitcnt lgkmcnt(6)
	v_mfma_f32_32x32x16_bf16 v[48:63], v[188:191], v[96:99], v[48:63]
	ds_read_b64_tr_b16 v[156:157], v171 offset:40960
	ds_read_b64_tr_b16 v[158:159], v171 offset:43008
	ds_read_b64_tr_b16 v[216:217], v171 offset:45056
	ds_read_b64_tr_b16 v[218:219], v171 offset:47104
	s_waitcnt lgkmcnt(9)
	v_mfma_f32_32x32x16_bf16 v[32:47], v[192:195], v[100:103], v[32:47]
	s_waitcnt lgkmcnt(8)
	v_mfma_f32_32x32x16_bf16 v[48:63], v[196:199], v[100:103], v[48:63]
	ds_read_b64_tr_b16 v[220:221], v171 offset:33280
	ds_read_b64_tr_b16 v[222:223], v171 offset:35328
	ds_read_b64_tr_b16 v[224:225], v171 offset:37376
	ds_read_b64_tr_b16 v[226:227], v171 offset:39424
	s_waitcnt lgkmcnt(10)
	v_mfma_f32_32x32x16_bf16 v[0:15], v[104:107], v[148:151], v[0:15]
	s_waitcnt lgkmcnt(8)
	v_mfma_f32_32x32x16_bf16 v[0:15], v[108:111], v[152:155], v[0:15]
	ds_read_b64_tr_b16 v[236:237], v171 offset:41472
	ds_read_b64_tr_b16 v[238:239], v171 offset:43520
	ds_read_b64_tr_b16 v[240:241], v171 offset:45568
	ds_read_b64_tr_b16 v[242:243], v171 offset:47616
	s_waitcnt lgkmcnt(10)
	v_mfma_f32_32x32x16_bf16 v[0:15], v[112:115], v[156:159], v[0:15]
	s_waitcnt lgkmcnt(8)
	v_mfma_f32_32x32x16_bf16 v[0:15], v[116:119], v[216:219], v[0:15]
	s_waitcnt lgkmcnt(6)
	v_mfma_f32_32x32x16_bf16 v[16:31], v[104:107], v[220:223], v[16:31]
	v_max3_f32 v174, v32, v33, v34
	v_max3_f32 v175, v48, v49, v50
	v_max3_f32 v174, v174, v35, v36
	v_max3_f32 v175, v175, v51, v52
	v_max3_f32 v174, v174, v37, v38
	v_max3_f32 v175, v175, v53, v54
	s_waitcnt lgkmcnt(4)
	v_mfma_f32_32x32x16_bf16 v[16:31], v[108:111], v[224:227], v[16:31]
	v_max3_f32 v174, v174, v39, v40
	v_max3_f32 v175, v175, v55, v56
	v_max3_f32 v174, v174, v41, v42
	v_max3_f32 v175, v175, v57, v58
	v_max3_f32 v174, v174, v43, v44
	v_max3_f32 v175, v175, v59, v60
	s_waitcnt lgkmcnt(2)
	v_mfma_f32_32x32x16_bf16 v[16:31], v[112:115], v[236:239], v[16:31]
	v_max3_f32 v174, v174, v45, v46
	v_max3_f32 v175, v175, v61, v62
	v_max3_f32 v174, v174, v47, v63
	v_max_f32_e32 v174, v174, v175
	s_waitcnt lgkmcnt(0)
	v_mfma_f32_32x32x16_bf16 v[16:31], v[116:119], v[240:243], v[16:31]
	v_mov_b32_e32 v175, v174
	s_nop 1
	v_permlane32_swap_b32_e32 v174, v175
	v_max_f32_e32 v174, v174, v175
	v_cmp_ge_f32_e32 vcc, s23, v174
	s_cmp_eq_u64 vcc, exec
	s_barrier
	s_cbranch_scc0 .Lat_rare2
.Lat_rare2_back:
	s_waitcnt vmcnt(0)
	ds_write_b128 v167, v[120:123] offset:13312
	ds_write_b128 v131, v[124:127] offset:16384
	ds_write_b128 v169, v[132:135] offset:13312
	v_exp_f32_e32 v32, v32
	v_exp_f32_e32 v48, v48
	v_exp_f32_e32 v33, v33
	v_exp_f32_e32 v49, v49
	v_exp_f32_e32 v34, v34
	v_exp_f32_e32 v50, v50
	v_exp_f32_e32 v35, v35
	v_exp_f32_e32 v51, v51
	v_exp_f32_e32 v36, v36
	v_exp_f32_e32 v52, v52
	v_exp_f32_e32 v37, v37
	v_exp_f32_e32 v53, v53
	v_exp_f32_e32 v38, v38
	v_exp_f32_e32 v54, v54
	v_exp_f32_e32 v39, v39
	v_exp_f32_e32 v55, v55
	v_exp_f32_e32 v40, v40
	v_exp_f32_e32 v56, v56
	v_exp_f32_e32 v41, v41
	v_exp_f32_e32 v57, v57
	v_exp_f32_e32 v42, v42
	v_exp_f32_e32 v58, v58
	v_exp_f32_e32 v43, v43
	v_exp_f32_e32 v59, v59
	v_exp_f32_e32 v44, v44
	v_exp_f32_e32 v60, v60
	v_exp_f32_e32 v45, v45
	v_exp_f32_e32 v61, v61
	v_exp_f32_e32 v46, v46
	v_exp_f32_e32 v62, v62
	v_exp_f32_e32 v47, v47
	v_exp_f32_e32 v63, v63
	s_waitcnt lgkmcnt(0)
	global_load_dwordx4 v[120:123], v129, s[4:5]
	global_load_dwordx4 v[124:127], v129, s[4:5] offset:128
	global_load_dwordx4 v[132:135], v130, s[6:7]
	s_add_u32 s4, s4, 0x40000
	s_addc_u32 s5, s5, 0
	s_add_u32 s6, s6, 0x1000
	s_addc_u32 s7, s7, 0
	v_add_f32_e32 v175, v32, v33
	v_add_f32_e32 v174, v48, v49
	v_add_f32_e32 v175, v175, v34
	v_add_f32_e32 v174, v174, v50
	v_add_f32_e32 v175, v175, v35
	v_add_f32_e32 v174, v174, v51
	v_add_f32_e32 v175, v175, v36
	v_add_f32_e32 v174, v174, v52
	v_add_f32_e32 v175, v175, v37
	v_add_f32_e32 v174, v174, v53
	v_add_f32_e32 v175, v175, v38
	v_add_f32_e32 v174, v174, v54
	v_add_f32_e32 v175, v175, v39
	v_add_f32_e32 v174, v174, v55
	v_add_f32_e32 v175, v175, v40
	v_add_f32_e32 v174, v174, v56
	v_add_f32_e32 v175, v175, v41
	v_add_f32_e32 v174, v174, v57
	v_add_f32_e32 v175, v175, v42
	v_add_f32_e32 v174, v174, v58
	v_add_f32_e32 v175, v175, v43
	v_add_f32_e32 v174, v174, v59
	v_add_f32_e32 v175, v175, v44
	v_add_f32_e32 v174, v174, v60
	v_add_f32_e32 v175, v175, v45
	v_add_f32_e32 v174, v174, v61
	v_add_f32_e32 v175, v175, v46
	v_add_f32_e32 v174, v174, v62
	v_add_f32_e32 v175, v175, v47
	v_add_f32_e32 v174, v174, v63
	v_add_f32_e32 v175, v175, v174
	v_add_f32_e32 v173, v173, v175
	v_cvt_pk_bf16_f32 v104, v32, v33
	v_cvt_pk_bf16_f32 v105, v34, v35
	v_cvt_pk_bf16_f32 v106, v36, v37
	v_cvt_pk_bf16_f32 v107, v38, v39
	v_cvt_pk_bf16_f32 v108, v40, v41
	v_cvt_pk_bf16_f32 v109, v42, v43
	v_cvt_pk_bf16_f32 v110, v44, v45
	v_cvt_pk_bf16_f32 v111, v46, v47
	v_cvt_pk_bf16_f32 v112, v48, v49
	v_cvt_pk_bf16_f32 v113, v50, v51
	v_cvt_pk_bf16_f32 v114, v52, v53
	v_cvt_pk_bf16_f32 v115, v54, v55
	v_cvt_pk_bf16_f32 v116, v56, v57
	v_cvt_pk_bf16_f32 v117, v58, v59
	v_cvt_pk_bf16_f32 v118, v60, v61
	v_cvt_pk_bf16_f32 v119, v62, v63
	ds_read_b128 v[184:187], v170 offset:0
	ds_read_b128 v[188:191], v170 offset:6656
	ds_read_b128 v[192:195], v170 offset:32
	ds_read_b128 v[196:199], v170 offset:6688
	s_barrier
; __device__ __forceinline__ void at_partialSM(f32x16& p0, f32x16& p1, float& m_reg, float& alpha, bool force) {
;   float pm = p0[0];
; #pragma unroll
;   for (int r = 1; r < 16; ++r) pm = fmaxf(pm, p0[r]);
; #pragma unroll
;   for (int r = 0; r < 16; ++r) pm = fmaxf(pm, p1[r]);
;   { auto rr = __builtin_amdgcn_permlane32_swap(__float_as_uint(pm), __float_as_uint(pm), false, false);
;     pm = fmaxf(__uint_as_float(rr[0]), __uint_as_float(rr[1])); }
;   if (__builtin_expect(!force && __all(pm <= AT_THR * 1.4426950408889634f), 1)) { alpha = 1.f; }
;   else {
;     const float dlt = force ? pm : fmaxf(pm, 0.f);
;     alpha = force ? 1.f : __builtin_amdgcn_exp2f(-dlt); m_reg += dlt;
; #pragma unroll
;     for (int r = 0; r < 16; ++r) { p0[r] -= dlt; p1[r] -= dlt; }
;   }
; #pragma unroll
;   for (int r = 0; r < 16; ++r) p0[r] = __builtin_amdgcn_exp2f(p0[r]);
; }
; __device__ __forceinline__ void at_finishSM(f32x16& p0, f32x16& p1, float alpha, float& l_reg, bf16x8& pa0, bf16x8& pa1, bf16x8& pa2, bf16x8& pa3) {
; #pragma unroll
;   for (int r = 0; r < 16; ++r) p1[r] = __builtin_amdgcn_exp2f(p1[r]);
;   float ps = 0;
; #pragma unroll
;   for (int r = 0; r < 16; ++r) ps += p0[r];
; #pragma unroll
;   for (int r = 0; r < 16; ++r) ps += p1[r];
;   { auto rr = __builtin_amdgcn_permlane32_swap(__float_as_uint(ps), __float_as_uint(ps), false, false);
;     ps = __uint_as_float(rr[0]) + __uint_as_float(rr[1]); }
;   l_reg = l_reg * alpha + ps;
;     ...
;   PK4(p0, 0, pa0); PK4(p0, 8, pa1); PK4(p1, 0, pa2); PK4(p1, 8, pa3);
; __device__ void phase_attn(const Params& p, char* lds) {
;     ...
;     for (int j = 1; j + 1 < NT; j += 2) {
;       SBAR(); at_qkt(pB0, pB1, K_lds + AT_SHMK, qr, r32, hi, -m_reg);
;       at_finishSM(pA0, pA1, alA, l_reg, pa0, pa1, pa2, pa3); SBAR();
;       SLOAD(1, (j + 2) * 64); SBAR();
;       pv_d0(o, vb0, pa0, pa1, pa2, pa3); at_partialSM(pB0, pB1, m_reg, alB, false);
;       __syncthreads(); SWAIT(); SWRITE(0, 0);
;       RESC(alB); __syncthreads();
;       SBAR(); at_qkt(pA0, pA1, K_lds, qr, r32, hi, -m_reg);
;       at_finishSM(pB0, pB1, alB, l_reg, pa0, pa1, pa2, pa3); SBAR();
;       if (j + 3 < NT) SLOAD(0, (j + 3) * 64); SBAR();
;       pv_d0(o, vb0 + AT_SHMV, pa0, pa1, pa2, pa3); at_partialSM(pA0, pA1, m_reg, alA, false);
;       __syncthreads(); SWAIT(); SWRITE(1, 1);
;       RESC(alA); __syncthreads();
;     }
	ds_read_b128 v[200:203], v170 offset:64
	ds_read_b128 v[204:207], v170 offset:6720
	s_waitcnt lgkmcnt(5)
	v_mfma_f32_32x32x16_bf16 v[32:47], v[184:187], v[80:83], v[64:79]
	s_waitcnt lgkmcnt(4)
	v_mfma_f32_32x32x16_bf16 v[48:63], v[188:191], v[80:83], v[64:79]
	ds_read_b128 v[208:211], v170 offset:96
	ds_read_b128 v[212:215], v170 offset:6752
	s_waitcnt lgkmcnt(5)
	v_mfma_f32_32x32x16_bf16 v[32:47], v[192:195], v[84:87], v[32:47]
	s_waitcnt lgkmcnt(4)
	v_mfma_f32_32x32x16_bf16 v[48:63], v[196:199], v[84:87], v[48:63]
	ds_read_b128 v[184:187], v170 offset:128
	ds_read_b128 v[188:191], v170 offset:6784
	s_waitcnt lgkmcnt(5)
	v_mfma_f32_32x32x16_bf16 v[32:47], v[200:203], v[88:91], v[32:47]
	s_waitcnt lgkmcnt(4)
	v_mfma_f32_32x32x16_bf16 v[48:63], v[204:207], v[88:91], v[48:63]
	ds_read_b128 v[192:195], v170 offset:160
	ds_read_b128 v[196:199], v170 offset:6816
	s_waitcnt lgkmcnt(5)
	v_mfma_f32_32x32x16_bf16 v[32:47], v[208:211], v[92:95], v[32:47]
	s_waitcnt lgkmcnt(4)
	v_mfma_f32_32x32x16_bf16 v[48:63], v[212:215], v[92:95], v[48:63]
	ds_read_b64_tr_b16 v[148:149], v171 offset:49152
	ds_read_b64_tr_b16 v[150:151], v171 offset:51200
	ds_read_b64_tr_b16 v[152:153], v171 offset:53248
	ds_read_b64_tr_b16 v[154:155], v171 offset:55296
	s_waitcnt lgkmcnt(7)
	v_mfma_f32_32x32x16_bf16 v[32:47], v[184:187], v[96:99], v[32:47]
	s_waitcnt lgkmcnt(6)
	v_mfma_f32_32x32x16_bf16 v[48:63], v[188:191], v[96:99], v[48:63]
	ds_read_b64_tr_b16 v[156:157], v171 offset:57344
	ds_read_b64_tr_b16 v[158:159], v171 offset:59392
	ds_read_b64_tr_b16 v[216:217], v171 offset:61440
	ds_read_b64_tr_b16 v[218:219], v171 offset:63488
	s_waitcnt lgkmcnt(9)
	v_mfma_f32_32x32x16_bf16 v[32:47], v[192:195], v[100:103], v[32:47]
	s_waitcnt lgkmcnt(8)
	v_mfma_f32_32x32x16_bf16 v[48:63], v[196:199], v[100:103], v[48:63]
	ds_read_b64_tr_b16 v[220:221], v171 offset:49664
	ds_read_b64_tr_b16 v[222:223], v171 offset:51712
	ds_read_b64_tr_b16 v[224:225], v171 offset:53760
	ds_read_b64_tr_b16 v[226:227], v171 offset:55808
	s_waitcnt lgkmcnt(10)
	v_mfma_f32_32x32x16_bf16 v[0:15], v[104:107], v[148:151], v[0:15]
	s_waitcnt lgkmcnt(8)
	v_mfma_f32_32x32x16_bf16 v[0:15], v[108:111], v[152:155], v[0:15]
	ds_read_b64_tr_b16 v[236:237], v171 offset:57856
	ds_read_b64_tr_b16 v[238:239], v171 offset:59904
	ds_read_b64_tr_b16 v[240:241], v171 offset:61952
	ds_read_b64_tr_b16 v[242:243], v171 offset:64000
	s_waitcnt lgkmcnt(10)
	v_mfma_f32_32x32x16_bf16 v[0:15], v[112:115], v[156:159], v[0:15]
	s_waitcnt lgkmcnt(8)
	v_mfma_f32_32x32x16_bf16 v[0:15], v[116:119], v[216:219], v[0:15]
	s_waitcnt lgkmcnt(6)
	v_mfma_f32_32x32x16_bf16 v[16:31], v[104:107], v[220:223], v[16:31]
	v_max3_f32 v174, v32, v33, v34
	v_max3_f32 v175, v48, v49, v50
	v_max3_f32 v174, v174, v35, v36
	v_max3_f32 v175, v175, v51, v52
	v_max3_f32 v174, v174, v37, v38
	v_max3_f32 v175, v175, v53, v54
	s_waitcnt lgkmcnt(4)
	v_mfma_f32_32x32x16_bf16 v[16:31], v[108:111], v[224:227], v[16:31]
	v_max3_f32 v174, v174, v39, v40
	v_max3_f32 v175, v175, v55, v56
	v_max3_f32 v174, v174, v41, v42
	v_max3_f32 v175, v175, v57, v58
	v_max3_f32 v174, v174, v43, v44
	v_max3_f32 v175, v175, v59, v60
	s_waitcnt lgkmcnt(2)
	v_mfma_f32_32x32x16_bf16 v[16:31], v[112:115], v[236:239], v[16:31]
	v_max3_f32 v174, v174, v45, v46
	v_max3_f32 v175, v175, v61, v62
	v_max3_f32 v174, v174, v47, v63
	v_max_f32_e32 v174, v174, v175
	s_waitcnt lgkmcnt(0)
	v_mfma_f32_32x32x16_bf16 v[16:31], v[116:119], v[240:243], v[16:31]
	v_mov_b32_e32 v175, v174
	s_nop 1
	v_permlane32_swap_b32_e32 v174, v175
	v_max_f32_e32 v174, v174, v175
	v_cmp_ge_f32_e32 vcc, s23, v174
	s_cmp_eq_u64 vcc, exec
	s_barrier
	s_cbranch_scc0 .Lat_rare3
.Lat_rare3_back:
	s_waitcnt vmcnt(0)
	ds_write_b128 v167, v[120:123] offset:26624
	ds_write_b128 v131, v[124:127] offset:32768
	ds_write_b128 v169, v[132:135] offset:26624
	v_exp_f32_e32 v32, v32
	v_exp_f32_e32 v48, v48
	v_exp_f32_e32 v33, v33
	v_exp_f32_e32 v49, v49
	v_exp_f32_e32 v34, v34
	v_exp_f32_e32 v50, v50
	v_exp_f32_e32 v35, v35
	v_exp_f32_e32 v51, v51
	v_exp_f32_e32 v36, v36
	v_exp_f32_e32 v52, v52
	v_exp_f32_e32 v37, v37
	v_exp_f32_e32 v53, v53
	v_exp_f32_e32 v38, v38
	v_exp_f32_e32 v54, v54
	v_exp_f32_e32 v39, v39
	v_exp_f32_e32 v55, v55
	v_exp_f32_e32 v40, v40
	v_exp_f32_e32 v56, v56
	v_exp_f32_e32 v41, v41
	v_exp_f32_e32 v57, v57
	v_exp_f32_e32 v42, v42
	v_exp_f32_e32 v58, v58
	v_exp_f32_e32 v43, v43
	v_exp_f32_e32 v59, v59
	v_exp_f32_e32 v44, v44
	v_exp_f32_e32 v60, v60
	v_exp_f32_e32 v45, v45
	v_exp_f32_e32 v61, v61
	v_exp_f32_e32 v46, v46
	v_exp_f32_e32 v62, v62
	v_exp_f32_e32 v47, v47
	v_exp_f32_e32 v63, v63
	s_waitcnt lgkmcnt(0)
	global_load_dwordx4 v[120:123], v129, s[4:5]
	global_load_dwordx4 v[124:127], v129, s[4:5] offset:128
	global_load_dwordx4 v[132:135], v130, s[6:7]
	s_add_u32 s4, s4, 0x40000
	s_addc_u32 s5, s5, 0
	s_add_u32 s6, s6, 0x1000
	s_addc_u32 s7, s7, 0
	v_add_f32_e32 v175, v32, v33
	v_add_f32_e32 v174, v48, v49
	v_add_f32_e32 v175, v175, v34
	v_add_f32_e32 v174, v174, v50
	v_add_f32_e32 v175, v175, v35
	v_add_f32_e32 v174, v174, v51
	v_add_f32_e32 v175, v175, v36
	v_add_f32_e32 v174, v174, v52
	v_add_f32_e32 v175, v175, v37
	v_add_f32_e32 v174, v174, v53
	v_add_f32_e32 v175, v175, v38
	v_add_f32_e32 v174, v174, v54
	v_add_f32_e32 v175, v175, v39
	v_add_f32_e32 v174, v174, v55
	v_add_f32_e32 v175, v175, v40
	v_add_f32_e32 v174, v174, v56
	v_add_f32_e32 v175, v175, v41
	v_add_f32_e32 v174, v174, v57
	v_add_f32_e32 v175, v175, v42
	v_add_f32_e32 v174, v174, v58
	v_add_f32_e32 v175, v175, v43
	v_add_f32_e32 v174, v174, v59
	v_add_f32_e32 v175, v175, v44
	v_add_f32_e32 v174, v174, v60
	v_add_f32_e32 v175, v175, v45
	v_add_f32_e32 v174, v174, v61
	v_add_f32_e32 v175, v175, v46
	v_add_f32_e32 v174, v174, v62
	v_add_f32_e32 v175, v175, v47
	v_add_f32_e32 v174, v174, v63
	v_add_f32_e32 v175, v175, v174
	v_add_f32_e32 v173, v173, v175
	v_cvt_pk_bf16_f32 v104, v32, v33
	v_cvt_pk_bf16_f32 v105, v34, v35
	v_cvt_pk_bf16_f32 v106, v36, v37
	v_cvt_pk_bf16_f32 v107, v38, v39
	v_cvt_pk_bf16_f32 v108, v40, v41
	v_cvt_pk_bf16_f32 v109, v42, v43
	v_cvt_pk_bf16_f32 v110, v44, v45
	v_cvt_pk_bf16_f32 v111, v46, v47
	v_cvt_pk_bf16_f32 v112, v48, v49
	v_cvt_pk_bf16_f32 v113, v50, v51
	v_cvt_pk_bf16_f32 v114, v52, v53
	v_cvt_pk_bf16_f32 v115, v54, v55
	v_cvt_pk_bf16_f32 v116, v56, v57
	v_cvt_pk_bf16_f32 v117, v58, v59
	v_cvt_pk_bf16_f32 v118, v60, v61
	v_cvt_pk_bf16_f32 v119, v62, v63
	ds_read_b128 v[184:187], v170 offset:13312
	ds_read_b128 v[188:191], v170 offset:19968
	ds_read_b128 v[192:195], v170 offset:13344
	ds_read_b128 v[196:199], v170 offset:20000
	s_barrier
; #define SBAR() __builtin_amdgcn_sched_barrier(0)
; #define RESC(a) do { if (__any((a) < 1.f)) { if (hi == 0) al_l[r32] = (a); asm volatile("s_waitcnt lgkmcnt(0)" ::: "memory"); \
;     _Pragma("unroll") for (int dd = 0; dd < 2; ++dd) _Pragma("unroll") for (int r = 0; r < 16; ++r) o[dd][r] *= al_l[crow(r, hi)]; } } while (0)
; __device__ __forceinline__ void at_partialSM(f32x16& p0, f32x16& p1, float& m_reg, float& alpha, bool force) {
;   float pm = p0[0];
; #pragma unroll
;   for (int r = 1; r < 16; ++r) pm = fmaxf(pm, p0[r]);
; #pragma unroll
;   for (int r = 0; r < 16; ++r) pm = fmaxf(pm, p1[r]);
;   { auto rr = __builtin_amdgcn_permlane32_swap(__float_as_uint(pm), __float_as_uint(pm), false, false);
;     pm = fmaxf(__uint_as_float(rr[0]), __uint_as_float(rr[1])); }
;   if (__builtin_expect(!force && __all(pm <= AT_THR * 1.4426950408889634f), 1)) { alpha = 1.f; }
;   else {
;     const float dlt = force ? pm : fmaxf(pm, 0.f);
;     alpha = force ? 1.f : __builtin_amdgcn_exp2f(-dlt); m_reg += dlt;
; #pragma unroll
;     for (int r = 0; r < 16; ++r) { p0[r] -= dlt; p1[r] -= dlt; }
;   }
; #pragma unroll
;   for (int r = 0; r < 16; ++r) p0[r] = __builtin_amdgcn_exp2f(p0[r]);
; }
; __device__ __forceinline__ void at_finishSM(f32x16& p0, f32x16& p1, float alpha, float& l_reg, bf16x8& pa0, bf16x8& pa1, bf16x8& pa2, bf16x8& pa3) {
; #pragma unroll
;   for (int r = 0; r < 16; ++r) p1[r] = __builtin_amdgcn_exp2f(p1[r]);
;   float ps = 0;
; #pragma unroll
;   for (int r = 0; r < 16; ++r) ps += p0[r];
; #pragma unroll
;   for (int r = 0; r < 16; ++r) ps += p1[r];
;   { auto rr = __builtin_amdgcn_permlane32_swap(__float_as_uint(ps), __float_as_uint(ps), false, false);
;     ps = __uint_as_float(rr[0]) + __uint_as_float(rr[1]); }
;   l_reg = l_reg * alpha + ps;
;     ...
;   PK4(p0, 0, pa0); PK4(p0, 8, pa1); PK4(p1, 0, pa2); PK4(p1, 8, pa3);
; __device__ void phase_attn(const Params& p, char* lds) {
;     ...
;     SBAR(); at_qkt(pB0, pB1, K_lds + AT_SHMK, qr, r32, hi, -m_reg);
;     at_finishSM(pA0, pA1, alA, l_reg, pa0, pa1, pa2, pa3); SBAR();
;     pv_d0(o, vb0, pa0, pa1, pa2, pa3); at_partialSM(pB0, pB1, m_reg, alB, false);
;     __syncthreads(); RESC(alB);
;     at_finishSM(pB0, pB1, alB, l_reg, pa0, pa1, pa2, pa3); SBAR();
;     pv_d0(o, vb0 + AT_SHMV, pa0, pa1, pa2, pa3);
	s_sub_u32 s13, s13, 1
	s_cmp_lg_u32 s13, 0
	s_cbranch_scc1 .Lat_loop
	ds_read_b128 v[200:203], v170 offset:13376
	ds_read_b128 v[204:207], v170 offset:20032
	s_waitcnt lgkmcnt(5)
	v_mfma_f32_32x32x16_bf16 v[32:47], v[184:187], v[80:83], v[64:79]
	s_waitcnt lgkmcnt(4)
	v_mfma_f32_32x32x16_bf16 v[48:63], v[188:191], v[80:83], v[64:79]
	ds_read_b128 v[208:211], v170 offset:13408
	ds_read_b128 v[212:215], v170 offset:20064
	s_waitcnt lgkmcnt(5)
	v_mfma_f32_32x32x16_bf16 v[32:47], v[192:195], v[84:87], v[32:47]
	s_waitcnt lgkmcnt(4)
	v_mfma_f32_32x32x16_bf16 v[48:63], v[196:199], v[84:87], v[48:63]
	ds_read_b128 v[184:187], v170 offset:13440
	ds_read_b128 v[188:191], v170 offset:20096
	s_waitcnt lgkmcnt(5)
	v_mfma_f32_32x32x16_bf16 v[32:47], v[200:203], v[88:91], v[32:47]
	s_waitcnt lgkmcnt(4)
	v_mfma_f32_32x32x16_bf16 v[48:63], v[204:207], v[88:91], v[48:63]
	ds_read_b128 v[192:195], v170 offset:13472
	ds_read_b128 v[196:199], v170 offset:20128
	s_waitcnt lgkmcnt(5)
	v_mfma_f32_32x32x16_bf16 v[32:47], v[208:211], v[92:95], v[32:47]
	s_waitcnt lgkmcnt(4)
	v_mfma_f32_32x32x16_bf16 v[48:63], v[212:215], v[92:95], v[48:63]
	ds_read_b64_tr_b16 v[148:149], v171 offset:0
	ds_read_b64_tr_b16 v[150:151], v171 offset:2048
	ds_read_b64_tr_b16 v[152:153], v171 offset:4096
	ds_read_b64_tr_b16 v[154:155], v171 offset:6144
	s_waitcnt lgkmcnt(7)
	v_mfma_f32_32x32x16_bf16 v[32:47], v[184:187], v[96:99], v[32:47]
	s_waitcnt lgkmcnt(6)
	v_mfma_f32_32x32x16_bf16 v[48:63], v[188:191], v[96:99], v[48:63]
	ds_read_b64_tr_b16 v[156:157], v171 offset:8192
	ds_read_b64_tr_b16 v[158:159], v171 offset:10240
	ds_read_b64_tr_b16 v[216:217], v171 offset:12288
	ds_read_b64_tr_b16 v[218:219], v171 offset:14336
	s_waitcnt lgkmcnt(9)
	v_mfma_f32_32x32x16_bf16 v[32:47], v[192:195], v[100:103], v[32:47]
	s_waitcnt lgkmcnt(8)
	v_mfma_f32_32x32x16_bf16 v[48:63], v[196:199], v[100:103], v[48:63]
	ds_read_b64_tr_b16 v[220:221], v171 offset:512
	ds_read_b64_tr_b16 v[222:223], v171 offset:2560
	ds_read_b64_tr_b16 v[224:225], v171 offset:4608
	ds_read_b64_tr_b16 v[226:227], v171 offset:6656
	s_waitcnt lgkmcnt(10)
	v_mfma_f32_32x32x16_bf16 v[0:15], v[104:107], v[148:151], v[0:15]
	s_waitcnt lgkmcnt(8)
	v_mfma_f32_32x32x16_bf16 v[0:15], v[108:111], v[152:155], v[0:15]
	ds_read_b64_tr_b16 v[236:237], v171 offset:8704
	ds_read_b64_tr_b16 v[238:239], v171 offset:10752
	ds_read_b64_tr_b16 v[240:241], v171 offset:12800
	ds_read_b64_tr_b16 v[242:243], v171 offset:14848
	s_waitcnt lgkmcnt(10)
	v_mfma_f32_32x32x16_bf16 v[0:15], v[112:115], v[156:159], v[0:15]
	s_waitcnt lgkmcnt(8)
	v_mfma_f32_32x32x16_bf16 v[0:15], v[116:119], v[216:219], v[0:15]
	s_waitcnt lgkmcnt(6)
	v_mfma_f32_32x32x16_bf16 v[16:31], v[104:107], v[220:223], v[16:31]
	v_max3_f32 v174, v32, v33, v34
	v_max3_f32 v175, v48, v49, v50
	v_max3_f32 v174, v174, v35, v36
	v_max3_f32 v175, v175, v51, v52
	v_max3_f32 v174, v174, v37, v38
	v_max3_f32 v175, v175, v53, v54
	s_waitcnt lgkmcnt(4)
	v_mfma_f32_32x32x16_bf16 v[16:31], v[108:111], v[224:227], v[16:31]
	v_max3_f32 v174, v174, v39, v40
	v_max3_f32 v175, v175, v55, v56
	v_max3_f32 v174, v174, v41, v42
	v_max3_f32 v175, v175, v57, v58
	v_max3_f32 v174, v174, v43, v44
	v_max3_f32 v175, v175, v59, v60
	s_waitcnt lgkmcnt(2)
	v_mfma_f32_32x32x16_bf16 v[16:31], v[112:115], v[236:239], v[16:31]
	v_max3_f32 v174, v174, v45, v46
	v_max3_f32 v175, v175, v61, v62
	v_max3_f32 v174, v174, v47, v63
	v_max_f32_e32 v174, v174, v175
	s_waitcnt lgkmcnt(0)
	v_mfma_f32_32x32x16_bf16 v[16:31], v[116:119], v[240:243], v[16:31]
	v_mov_b32_e32 v175, v174
	s_nop 1
	v_permlane32_swap_b32_e32 v174, v175
	v_max_f32_e32 v174, v174, v175
	v_cmp_ge_f32_e32 vcc, s23, v174
	s_cmp_eq_u64 vcc, exec
	s_barrier
	s_cbranch_scc0 .Lat_rare_t129
.Lat_rare_t129_back:
	s_waitcnt vmcnt(0)
	ds_write_b128 v167, v[120:123] offset:39936
	ds_write_b128 v131, v[124:127] offset:49152
	ds_write_b128 v169, v[132:135] offset:39936
	v_exp_f32_e32 v32, v32
	v_exp_f32_e32 v48, v48
	v_exp_f32_e32 v33, v33
	v_exp_f32_e32 v49, v49
	v_exp_f32_e32 v34, v34
	v_exp_f32_e32 v50, v50
	v_exp_f32_e32 v35, v35
	v_exp_f32_e32 v51, v51
	v_exp_f32_e32 v36, v36
	v_exp_f32_e32 v52, v52
	v_exp_f32_e32 v37, v37
	v_exp_f32_e32 v53, v53
	v_exp_f32_e32 v38, v38
	v_exp_f32_e32 v54, v54
	v_exp_f32_e32 v39, v39
	v_exp_f32_e32 v55, v55
	v_exp_f32_e32 v40, v40
	v_exp_f32_e32 v56, v56
	v_exp_f32_e32 v41, v41
	v_exp_f32_e32 v57, v57
	v_exp_f32_e32 v42, v42
	v_exp_f32_e32 v58, v58
	v_exp_f32_e32 v43, v43
	v_exp_f32_e32 v59, v59
	v_exp_f32_e32 v44, v44
	v_exp_f32_e32 v60, v60
	v_exp_f32_e32 v45, v45
	v_exp_f32_e32 v61, v61
	v_exp_f32_e32 v46, v46
	v_exp_f32_e32 v62, v62
	v_exp_f32_e32 v47, v47
	v_exp_f32_e32 v63, v63
	v_add_f32_e32 v175, v32, v33
	v_add_f32_e32 v174, v48, v49
	v_add_f32_e32 v175, v175, v34
	v_add_f32_e32 v174, v174, v50
	v_add_f32_e32 v175, v175, v35
	v_add_f32_e32 v174, v174, v51
	v_add_f32_e32 v175, v175, v36
	v_add_f32_e32 v174, v174, v52
	v_add_f32_e32 v175, v175, v37
	v_add_f32_e32 v174, v174, v53
	v_add_f32_e32 v175, v175, v38
	v_add_f32_e32 v174, v174, v54
	v_add_f32_e32 v175, v175, v39
	v_add_f32_e32 v174, v174, v55
	v_add_f32_e32 v175, v175, v40
	v_add_f32_e32 v174, v174, v56
	v_add_f32_e32 v175, v175, v41
	v_add_f32_e32 v174, v174, v57
	v_add_f32_e32 v175, v175, v42
	v_add_f32_e32 v174, v174, v58
	v_add_f32_e32 v175, v175, v43
	v_add_f32_e32 v174, v174, v59
	v_add_f32_e32 v175, v175, v44
	v_add_f32_e32 v174, v174, v60
	v_add_f32_e32 v175, v175, v45
	v_add_f32_e32 v174, v174, v61
	v_add_f32_e32 v175, v175, v46
	v_add_f32_e32 v174, v174, v62
	v_add_f32_e32 v175, v175, v47
	v_add_f32_e32 v174, v174, v63
	v_add_f32_e32 v175, v175, v174
	v_add_f32_e32 v173, v173, v175
	v_cvt_pk_bf16_f32 v104, v32, v33
	v_cvt_pk_bf16_f32 v105, v34, v35
	v_cvt_pk_bf16_f32 v106, v36, v37
	v_cvt_pk_bf16_f32 v107, v38, v39
	v_cvt_pk_bf16_f32 v108, v40, v41
	v_cvt_pk_bf16_f32 v109, v42, v43
	v_cvt_pk_bf16_f32 v110, v44, v45
	v_cvt_pk_bf16_f32 v111, v46, v47
	v_cvt_pk_bf16_f32 v112, v48, v49
	v_cvt_pk_bf16_f32 v113, v50, v51
	v_cvt_pk_bf16_f32 v114, v52, v53
	v_cvt_pk_bf16_f32 v115, v54, v55
	v_cvt_pk_bf16_f32 v116, v56, v57
	v_cvt_pk_bf16_f32 v117, v58, v59
	v_cvt_pk_bf16_f32 v118, v60, v61
	v_cvt_pk_bf16_f32 v119, v62, v63
	ds_read_b128 v[184:187], v170 offset:26624
	ds_read_b128 v[188:191], v170 offset:33280
	ds_read_b128 v[192:195], v170 offset:26656
	ds_read_b128 v[196:199], v170 offset:33312
	s_waitcnt lgkmcnt(4)
	s_barrier
; #define SBAR() __builtin_amdgcn_sched_barrier(0)
; #define RESC(a) do { if (__any((a) < 1.f)) { if (hi == 0) al_l[r32] = (a); asm volatile("s_waitcnt lgkmcnt(0)" ::: "memory"); \
;     _Pragma("unroll") for (int dd = 0; dd < 2; ++dd) _Pragma("unroll") for (int r = 0; r < 16; ++r) o[dd][r] *= al_l[crow(r, hi)]; } } while (0)
; __device__ __forceinline__ void at_partialSM(f32x16& p0, f32x16& p1, float& m_reg, float& alpha, bool force) {
;   float pm = p0[0];
; #pragma unroll
;   for (int r = 1; r < 16; ++r) pm = fmaxf(pm, p0[r]);
; #pragma unroll
;   for (int r = 0; r < 16; ++r) pm = fmaxf(pm, p1[r]);
;   { auto rr = __builtin_amdgcn_permlane32_swap(__float_as_uint(pm), __float_as_uint(pm), false, false);
;     pm = fmaxf(__uint_as_float(rr[0]), __uint_as_float(rr[1])); }
;   if (__builtin_expect(!force && __all(pm <= AT_THR * 1.4426950408889634f), 1)) { alpha = 1.f; }
;   else {
;     const float dlt = force ? pm : fmaxf(pm, 0.f);
;     alpha = force ? 1.f : __builtin_amdgcn_exp2f(-dlt); m_reg += dlt;
; #pragma unroll
;     for (int r = 0; r < 16; ++r) { p0[r] -= dlt; p1[r] -= dlt; }
;   }
; #pragma unroll
;   for (int r = 0; r < 16; ++r) p0[r] = __builtin_amdgcn_exp2f(p0[r]);
; }
; __device__ __forceinline__ void at_finishSM(f32x16& p0, f32x16& p1, float alpha, float& l_reg, bf16x8& pa0, bf16x8& pa1, bf16x8& pa2, bf16x8& pa3) {
; #pragma unroll
;   for (int r = 0; r < 16; ++r) p1[r] = __builtin_amdgcn_exp2f(p1[r]);
;   float ps = 0;
; #pragma unroll
;   for (int r = 0; r < 16; ++r) ps += p0[r];
; #pragma unroll
;   for (int r = 0; r < 16; ++r) ps += p1[r];
;   { auto rr = __builtin_amdgcn_permlane32_swap(__float_as_uint(ps), __float_as_uint(ps), false, false);
;     ps = __uint_as_float(rr[0]) + __uint_as_float(rr[1]); }
;   l_reg = l_reg * alpha + ps;
;     ...
;   PK4(p0, 0, pa0); PK4(p0, 8, pa1); PK4(p1, 0, pa2); PK4(p1, 8, pa3);
; __device__ void phase_attn(const Params& p, char* lds) {
;     ...
;     SBAR(); at_qkt(pB0, pB1, K_lds + AT_SHMK, qr, r32, hi, -m_reg);
;     at_finishSM(pA0, pA1, alA, l_reg, pa0, pa1, pa2, pa3); SBAR();
;     pv_d0(o, vb0, pa0, pa1, pa2, pa3); at_partialSM(pB0, pB1, m_reg, alB, false);
;     __syncthreads(); RESC(alB);
;     at_finishSM(pB0, pB1, alB, l_reg, pa0, pa1, pa2, pa3); SBAR();
;     pv_d0(o, vb0 + AT_SHMV, pa0, pa1, pa2, pa3);
	ds_read_b128 v[200:203], v170 offset:26688
	ds_read_b128 v[204:207], v170 offset:33344
	s_waitcnt lgkmcnt(5)
	v_mfma_f32_32x32x16_bf16 v[32:47], v[184:187], v[80:83], v[64:79]
	s_waitcnt lgkmcnt(4)
	v_mfma_f32_32x32x16_bf16 v[48:63], v[188:191], v[80:83], v[64:79]
	ds_read_b128 v[208:211], v170 offset:26720
	ds_read_b128 v[212:215], v170 offset:33376
	s_waitcnt lgkmcnt(5)
	v_mfma_f32_32x32x16_bf16 v[32:47], v[192:195], v[84:87], v[32:47]
	s_waitcnt lgkmcnt(4)
	v_mfma_f32_32x32x16_bf16 v[48:63], v[196:199], v[84:87], v[48:63]
	ds_read_b128 v[184:187], v170 offset:26752
	ds_read_b128 v[188:191], v170 offset:33408
	s_waitcnt lgkmcnt(5)
	v_mfma_f32_32x32x16_bf16 v[32:47], v[200:203], v[88:91], v[32:47]
	s_waitcnt lgkmcnt(4)
	v_mfma_f32_32x32x16_bf16 v[48:63], v[204:207], v[88:91], v[48:63]
	ds_read_b128 v[192:195], v170 offset:26784
	ds_read_b128 v[196:199], v170 offset:33440
	s_waitcnt lgkmcnt(5)
	v_mfma_f32_32x32x16_bf16 v[32:47], v[208:211], v[92:95], v[32:47]
	s_waitcnt lgkmcnt(4)
	v_mfma_f32_32x32x16_bf16 v[48:63], v[212:215], v[92:95], v[48:63]
	ds_read_b64_tr_b16 v[148:149], v171 offset:16384
	ds_read_b64_tr_b16 v[150:151], v171 offset:18432
	ds_read_b64_tr_b16 v[152:153], v171 offset:20480
	ds_read_b64_tr_b16 v[154:155], v171 offset:22528
	s_waitcnt lgkmcnt(7)
	v_mfma_f32_32x32x16_bf16 v[32:47], v[184:187], v[96:99], v[32:47]
	s_waitcnt lgkmcnt(6)
	v_mfma_f32_32x32x16_bf16 v[48:63], v[188:191], v[96:99], v[48:63]
	ds_read_b64_tr_b16 v[156:157], v171 offset:24576
	ds_read_b64_tr_b16 v[158:159], v171 offset:26624
	ds_read_b64_tr_b16 v[216:217], v171 offset:28672
	ds_read_b64_tr_b16 v[218:219], v171 offset:30720
	s_waitcnt lgkmcnt(9)
	v_mfma_f32_32x32x16_bf16 v[32:47], v[192:195], v[100:103], v[32:47]
	s_waitcnt lgkmcnt(8)
	v_mfma_f32_32x32x16_bf16 v[48:63], v[196:199], v[100:103], v[48:63]
	ds_read_b64_tr_b16 v[220:221], v171 offset:16896
	ds_read_b64_tr_b16 v[222:223], v171 offset:18944
	ds_read_b64_tr_b16 v[224:225], v171 offset:20992
	ds_read_b64_tr_b16 v[226:227], v171 offset:23040
	s_waitcnt lgkmcnt(10)
	v_mfma_f32_32x32x16_bf16 v[0:15], v[104:107], v[148:151], v[0:15]
	s_waitcnt lgkmcnt(8)
	v_mfma_f32_32x32x16_bf16 v[0:15], v[108:111], v[152:155], v[0:15]
	ds_read_b64_tr_b16 v[236:237], v171 offset:25088
	ds_read_b64_tr_b16 v[238:239], v171 offset:27136
	ds_read_b64_tr_b16 v[240:241], v171 offset:29184
	ds_read_b64_tr_b16 v[242:243], v171 offset:31232
	s_waitcnt lgkmcnt(10)
	v_mfma_f32_32x32x16_bf16 v[0:15], v[112:115], v[156:159], v[0:15]
	s_waitcnt lgkmcnt(8)
	v_mfma_f32_32x32x16_bf16 v[0:15], v[116:119], v[216:219], v[0:15]
	s_waitcnt lgkmcnt(6)
	v_mfma_f32_32x32x16_bf16 v[16:31], v[104:107], v[220:223], v[16:31]
	v_max3_f32 v174, v32, v33, v34
	v_max3_f32 v175, v48, v49, v50
	v_max3_f32 v174, v174, v35, v36
	v_max3_f32 v175, v175, v51, v52
	v_max3_f32 v174, v174, v37, v38
	v_max3_f32 v175, v175, v53, v54
	s_waitcnt lgkmcnt(4)
	v_mfma_f32_32x32x16_bf16 v[16:31], v[108:111], v[224:227], v[16:31]
	v_max3_f32 v174, v174, v39, v40
	v_max3_f32 v175, v175, v55, v56
	v_max3_f32 v174, v174, v41, v42
	v_max3_f32 v175, v175, v57, v58
	v_max3_f32 v174, v174, v43, v44
	v_max3_f32 v175, v175, v59, v60
	s_waitcnt lgkmcnt(2)
	v_mfma_f32_32x32x16_bf16 v[16:31], v[112:115], v[236:239], v[16:31]
	v_max3_f32 v174, v174, v45, v46
	v_max3_f32 v175, v175, v61, v62
	v_max3_f32 v174, v174, v47, v63
	v_max_f32_e32 v174, v174, v175
	s_waitcnt lgkmcnt(0)
	v_mfma_f32_32x32x16_bf16 v[16:31], v[116:119], v[240:243], v[16:31]
	v_mov_b32_e32 v175, v174
	s_nop 1
	v_permlane32_swap_b32_e32 v174, v175
	v_max_f32_e32 v174, v174, v175
	v_cmp_ge_f32_e32 vcc, s23, v174
	s_cmp_eq_u64 vcc, exec
	s_barrier
	s_cbranch_scc0 .Lat_rare_t130
.Lat_rare_t130_back:
	v_exp_f32_e32 v32, v32
	v_exp_f32_e32 v48, v48
	v_exp_f32_e32 v33, v33
	v_exp_f32_e32 v49, v49
	v_exp_f32_e32 v34, v34
	v_exp_f32_e32 v50, v50
	v_exp_f32_e32 v35, v35
	v_exp_f32_e32 v51, v51
	v_exp_f32_e32 v36, v36
	v_exp_f32_e32 v52, v52
	v_exp_f32_e32 v37, v37
	v_exp_f32_e32 v53, v53
	v_exp_f32_e32 v38, v38
	v_exp_f32_e32 v54, v54
	v_exp_f32_e32 v39, v39
	v_exp_f32_e32 v55, v55
	v_exp_f32_e32 v40, v40
	v_exp_f32_e32 v56, v56
	v_exp_f32_e32 v41, v41
	v_exp_f32_e32 v57, v57
	v_exp_f32_e32 v42, v42
	v_exp_f32_e32 v58, v58
	v_exp_f32_e32 v43, v43
	v_exp_f32_e32 v59, v59
	v_exp_f32_e32 v44, v44
	v_exp_f32_e32 v60, v60
	v_exp_f32_e32 v45, v45
	v_exp_f32_e32 v61, v61
	v_exp_f32_e32 v46, v46
	v_exp_f32_e32 v62, v62
	v_exp_f32_e32 v47, v47
	v_exp_f32_e32 v63, v63
	v_add_f32_e32 v175, v32, v33
	v_add_f32_e32 v174, v48, v49
	v_add_f32_e32 v175, v175, v34
	v_add_f32_e32 v174, v174, v50
	v_add_f32_e32 v175, v175, v35
	v_add_f32_e32 v174, v174, v51
	v_add_f32_e32 v175, v175, v36
	v_add_f32_e32 v174, v174, v52
	v_add_f32_e32 v175, v175, v37
	v_add_f32_e32 v174, v174, v53
	v_add_f32_e32 v175, v175, v38
	v_add_f32_e32 v174, v174, v54
	v_add_f32_e32 v175, v175, v39
	v_add_f32_e32 v174, v174, v55
	v_add_f32_e32 v175, v175, v40
	v_add_f32_e32 v174, v174, v56
	v_add_f32_e32 v175, v175, v41
	v_add_f32_e32 v174, v174, v57
	v_add_f32_e32 v175, v175, v42
	v_add_f32_e32 v174, v174, v58
	v_add_f32_e32 v175, v175, v43
	v_add_f32_e32 v174, v174, v59
	v_add_f32_e32 v175, v175, v44
	v_add_f32_e32 v174, v174, v60
	v_add_f32_e32 v175, v175, v45
	v_add_f32_e32 v174, v174, v61
	v_add_f32_e32 v175, v175, v46
	v_add_f32_e32 v174, v174, v62
	v_add_f32_e32 v175, v175, v47
	v_add_f32_e32 v174, v174, v63
	v_add_f32_e32 v175, v175, v174
	v_add_f32_e32 v173, v173, v175
	v_cvt_pk_bf16_f32 v104, v32, v33
	v_cvt_pk_bf16_f32 v105, v34, v35
	v_cvt_pk_bf16_f32 v106, v36, v37
	v_cvt_pk_bf16_f32 v107, v38, v39
	v_cvt_pk_bf16_f32 v108, v40, v41
	v_cvt_pk_bf16_f32 v109, v42, v43
	v_cvt_pk_bf16_f32 v110, v44, v45
	v_cvt_pk_bf16_f32 v111, v46, v47
	v_cvt_pk_bf16_f32 v112, v48, v49
	v_cvt_pk_bf16_f32 v113, v50, v51
	v_cvt_pk_bf16_f32 v114, v52, v53
	v_cvt_pk_bf16_f32 v115, v54, v55
	v_cvt_pk_bf16_f32 v116, v56, v57
	v_cvt_pk_bf16_f32 v117, v58, v59
	v_cvt_pk_bf16_f32 v118, v60, v61
	v_cvt_pk_bf16_f32 v119, v62, v63
	ds_read_b128 v[184:187], v170 offset:39936
	ds_read_b128 v[188:191], v170 offset:46592
	ds_read_b128 v[192:195], v170 offset:39968
	ds_read_b128 v[196:199], v170 offset:46624
	s_barrier
; #define SBAR() __builtin_amdgcn_sched_barrier(0)
; #define RESC(a) do { if (__any((a) < 1.f)) { if (hi == 0) al_l[r32] = (a); asm volatile("s_waitcnt lgkmcnt(0)" ::: "memory"); \
;     _Pragma("unroll") for (int dd = 0; dd < 2; ++dd) _Pragma("unroll") for (int r = 0; r < 16; ++r) o[dd][r] *= al_l[crow(r, hi)]; } } while (0)
; __device__ __forceinline__ void at_partialSM(f32x16& p0, f32x16& p1, float& m_reg, float& alpha, bool force) {
;   float pm = p0[0];
; #pragma unroll
;   for (int r = 1; r < 16; ++r) pm = fmaxf(pm, p0[r]);
; #pragma unroll
;   for (int r = 0; r < 16; ++r) pm = fmaxf(pm, p1[r]);
;   { auto rr = __builtin_amdgcn_permlane32_swap(__float_as_uint(pm), __float_as_uint(pm), false, false);
;     pm = fmaxf(__uint_as_float(rr[0]), __uint_as_float(rr[1])); }
;   if (__builtin_expect(!force && __all(pm <= AT_THR * 1.4426950408889634f), 1)) { alpha = 1.f; }
;   else {
;     const float dlt = force ? pm : fmaxf(pm, 0.f);
;     alpha = force ? 1.f : __builtin_amdgcn_exp2f(-dlt); m_reg += dlt;
; #pragma unroll
;     for (int r = 0; r < 16; ++r) { p0[r] -= dlt; p1[r] -= dlt; }
;   }
; #pragma unroll
;   for (int r = 0; r < 16; ++r) p0[r] = __builtin_amdgcn_exp2f(p0[r]);
; }
; __device__ __forceinline__ void at_finishSM(f32x16& p0, f32x16& p1, float alpha, float& l_reg, bf16x8& pa0, bf16x8& pa1, bf16x8& pa2, bf16x8& pa3) {
; #pragma unroll
;   for (int r = 0; r < 16; ++r) p1[r] = __builtin_amdgcn_exp2f(p1[r]);
;   float ps = 0;
; #pragma unroll
;   for (int r = 0; r < 16; ++r) ps += p0[r];
; #pragma unroll
;   for (int r = 0; r < 16; ++r) ps += p1[r];
;   { auto rr = __builtin_amdgcn_permlane32_swap(__float_as_uint(ps), __float_as_uint(ps), false, false);
;     ps = __uint_as_float(rr[0]) + __uint_as_float(rr[1]); }
;   l_reg = l_reg * alpha + ps;
;     ...
;   PK4(p0, 0, pa0); PK4(p0, 8, pa1); PK4(p1, 0, pa2); PK4(p1, 8, pa3);
; __device__ void phase_attn(const Params& p, char* lds) {
;     ...
;     SBAR(); at_qkt(pB0, pB1, K_lds + AT_SHMK, qr, r32, hi, -m_reg);
;     at_finishSM(pA0, pA1, alA, l_reg, pa0, pa1, pa2, pa3); SBAR();
;     pv_d0(o, vb0, pa0, pa1, pa2, pa3); at_partialSM(pB0, pB1, m_reg, alB, false);
;     __syncthreads(); RESC(alB);
;     at_finishSM(pB0, pB1, alB, l_reg, pa0, pa1, pa2, pa3); SBAR();
;     pv_d0(o, vb0 + AT_SHMV, pa0, pa1, pa2, pa3);
	ds_read_b128 v[200:203], v170 offset:40000
	ds_read_b128 v[204:207], v170 offset:46656
	s_waitcnt lgkmcnt(5)
	v_mfma_f32_32x32x16_bf16 v[32:47], v[184:187], v[80:83], v[64:79]
	s_waitcnt lgkmcnt(4)
	v_mfma_f32_32x32x16_bf16 v[48:63], v[188:191], v[80:83], v[64:79]
	ds_read_b128 v[208:211], v170 offset:40032
	ds_read_b128 v[212:215], v170 offset:46688
	s_waitcnt lgkmcnt(5)
	v_mfma_f32_32x32x16_bf16 v[32:47], v[192:195], v[84:87], v[32:47]
	s_waitcnt lgkmcnt(4)
	v_mfma_f32_32x32x16_bf16 v[48:63], v[196:199], v[84:87], v[48:63]
	ds_read_b128 v[184:187], v170 offset:40064
	ds_read_b128 v[188:191], v170 offset:46720
	s_waitcnt lgkmcnt(5)
	v_mfma_f32_32x32x16_bf16 v[32:47], v[200:203], v[88:91], v[32:47]
	s_waitcnt lgkmcnt(4)
	v_mfma_f32_32x32x16_bf16 v[48:63], v[204:207], v[88:91], v[48:63]
	ds_read_b128 v[192:195], v170 offset:40096
	ds_read_b128 v[196:199], v170 offset:46752
	s_waitcnt lgkmcnt(5)
	v_mfma_f32_32x32x16_bf16 v[32:47], v[208:211], v[92:95], v[32:47]
	s_waitcnt lgkmcnt(4)
	v_mfma_f32_32x32x16_bf16 v[48:63], v[212:215], v[92:95], v[48:63]
	ds_read_b64_tr_b16 v[148:149], v171 offset:32768
	ds_read_b64_tr_b16 v[150:151], v171 offset:34816
	ds_read_b64_tr_b16 v[152:153], v171 offset:36864
	ds_read_b64_tr_b16 v[154:155], v171 offset:38912
	s_waitcnt lgkmcnt(7)
	v_mfma_f32_32x32x16_bf16 v[32:47], v[184:187], v[96:99], v[32:47]
	s_waitcnt lgkmcnt(6)
	v_mfma_f32_32x32x16_bf16 v[48:63], v[188:191], v[96:99], v[48:63]
	ds_read_b64_tr_b16 v[156:157], v171 offset:40960
	ds_read_b64_tr_b16 v[158:159], v171 offset:43008
	ds_read_b64_tr_b16 v[216:217], v171 offset:45056
	ds_read_b64_tr_b16 v[218:219], v171 offset:47104
	s_waitcnt lgkmcnt(9)
	v_mfma_f32_32x32x16_bf16 v[32:47], v[192:195], v[100:103], v[32:47]
	s_waitcnt lgkmcnt(8)
	v_mfma_f32_32x32x16_bf16 v[48:63], v[196:199], v[100:103], v[48:63]
	ds_read_b64_tr_b16 v[220:221], v171 offset:33280
	ds_read_b64_tr_b16 v[222:223], v171 offset:35328
	ds_read_b64_tr_b16 v[224:225], v171 offset:37376
	ds_read_b64_tr_b16 v[226:227], v171 offset:39424
	s_waitcnt lgkmcnt(10)
	v_mfma_f32_32x32x16_bf16 v[0:15], v[104:107], v[148:151], v[0:15]
	s_waitcnt lgkmcnt(8)
	v_mfma_f32_32x32x16_bf16 v[0:15], v[108:111], v[152:155], v[0:15]
	ds_read_b64_tr_b16 v[236:237], v171 offset:41472
	ds_read_b64_tr_b16 v[238:239], v171 offset:43520
	ds_read_b64_tr_b16 v[240:241], v171 offset:45568
	ds_read_b64_tr_b16 v[242:243], v171 offset:47616
	s_waitcnt lgkmcnt(10)
	v_mfma_f32_32x32x16_bf16 v[0:15], v[112:115], v[156:159], v[0:15]
	s_waitcnt lgkmcnt(8)
	v_mfma_f32_32x32x16_bf16 v[0:15], v[116:119], v[216:219], v[0:15]
	s_waitcnt lgkmcnt(6)
	v_mfma_f32_32x32x16_bf16 v[16:31], v[104:107], v[220:223], v[16:31]
	v_max3_f32 v174, v32, v33, v34
	v_max3_f32 v175, v48, v49, v50
	v_max3_f32 v174, v174, v35, v36
	v_max3_f32 v175, v175, v51, v52
	v_max3_f32 v174, v174, v37, v38
	v_max3_f32 v175, v175, v53, v54
	s_waitcnt lgkmcnt(4)
	v_mfma_f32_32x32x16_bf16 v[16:31], v[108:111], v[224:227], v[16:31]
	v_max3_f32 v174, v174, v39, v40
	v_max3_f32 v175, v175, v55, v56
	v_max3_f32 v174, v174, v41, v42
	v_max3_f32 v175, v175, v57, v58
	v_max3_f32 v174, v174, v43, v44
	v_max3_f32 v175, v175, v59, v60
	s_waitcnt lgkmcnt(2)
	v_mfma_f32_32x32x16_bf16 v[16:31], v[112:115], v[236:239], v[16:31]
	v_max3_f32 v174, v174, v45, v46
	v_max3_f32 v175, v175, v61, v62
	v_max3_f32 v174, v174, v47, v63
	v_max_f32_e32 v174, v174, v175
	s_waitcnt lgkmcnt(0)
	v_mfma_f32_32x32x16_bf16 v[16:31], v[116:119], v[240:243], v[16:31]
	v_mov_b32_e32 v175, v174
	s_nop 1
	v_permlane32_swap_b32_e32 v174, v175
	v_max_f32_e32 v174, v174, v175
	v_cmp_ge_f32_e32 vcc, s23, v174
	s_cmp_eq_u64 vcc, exec
	s_barrier
	s_cbranch_scc0 .Lat_rare_t131
.Lat_rare_t131_back:
	v_exp_f32_e32 v32, v32
	v_exp_f32_e32 v48, v48
	v_exp_f32_e32 v33, v33
	v_exp_f32_e32 v49, v49
	v_exp_f32_e32 v34, v34
	v_exp_f32_e32 v50, v50
	v_exp_f32_e32 v35, v35
	v_exp_f32_e32 v51, v51
	v_exp_f32_e32 v36, v36
	v_exp_f32_e32 v52, v52
	v_exp_f32_e32 v37, v37
	v_exp_f32_e32 v53, v53
	v_exp_f32_e32 v38, v38
	v_exp_f32_e32 v54, v54
	v_exp_f32_e32 v39, v39
	v_exp_f32_e32 v55, v55
	v_exp_f32_e32 v40, v40
	v_exp_f32_e32 v56, v56
	v_exp_f32_e32 v41, v41
	v_exp_f32_e32 v57, v57
	v_exp_f32_e32 v42, v42
	v_exp_f32_e32 v58, v58
	v_exp_f32_e32 v43, v43
	v_exp_f32_e32 v59, v59
	v_exp_f32_e32 v44, v44
	v_exp_f32_e32 v60, v60
	v_exp_f32_e32 v45, v45
	v_exp_f32_e32 v61, v61
	v_exp_f32_e32 v46, v46
	v_exp_f32_e32 v62, v62
	v_exp_f32_e32 v47, v47
	v_exp_f32_e32 v63, v63
	v_add_f32_e32 v175, v32, v33
	v_add_f32_e32 v174, v48, v49
	v_add_f32_e32 v175, v175, v34
	v_add_f32_e32 v174, v174, v50
	v_add_f32_e32 v175, v175, v35
	v_add_f32_e32 v174, v174, v51
	v_add_f32_e32 v175, v175, v36
	v_add_f32_e32 v174, v174, v52
	v_add_f32_e32 v175, v175, v37
	v_add_f32_e32 v174, v174, v53
	v_add_f32_e32 v175, v175, v38
	v_add_f32_e32 v174, v174, v54
	v_add_f32_e32 v175, v175, v39
	v_add_f32_e32 v174, v174, v55
	v_add_f32_e32 v175, v175, v40
	v_add_f32_e32 v174, v174, v56
	v_add_f32_e32 v175, v175, v41
	v_add_f32_e32 v174, v174, v57
	v_add_f32_e32 v175, v175, v42
	v_add_f32_e32 v174, v174, v58
	v_add_f32_e32 v175, v175, v43
	v_add_f32_e32 v174, v174, v59
	v_add_f32_e32 v175, v175, v44
	v_add_f32_e32 v174, v174, v60
	v_add_f32_e32 v175, v175, v45
	v_add_f32_e32 v174, v174, v61
	v_add_f32_e32 v175, v175, v46
	v_add_f32_e32 v174, v174, v62
	v_add_f32_e32 v175, v175, v47
	v_add_f32_e32 v174, v174, v63
	v_add_f32_e32 v175, v175, v174
	v_add_f32_e32 v173, v173, v175
	v_cvt_pk_bf16_f32 v104, v32, v33
	v_cvt_pk_bf16_f32 v105, v34, v35
	v_cvt_pk_bf16_f32 v106, v36, v37
	v_cvt_pk_bf16_f32 v107, v38, v39
	v_cvt_pk_bf16_f32 v108, v40, v41
	v_cvt_pk_bf16_f32 v109, v42, v43
	v_cvt_pk_bf16_f32 v110, v44, v45
	v_cvt_pk_bf16_f32 v111, v46, v47
	v_cvt_pk_bf16_f32 v112, v48, v49
	v_cvt_pk_bf16_f32 v113, v50, v51
	v_cvt_pk_bf16_f32 v114, v52, v53
	v_cvt_pk_bf16_f32 v115, v54, v55
	v_cvt_pk_bf16_f32 v116, v56, v57
	v_cvt_pk_bf16_f32 v117, v58, v59
	v_cvt_pk_bf16_f32 v118, v60, v61
	v_cvt_pk_bf16_f32 v119, v62, v63
	s_barrier
; __device__ __forceinline__ int crow(int r, int hi) { return (r & 3) + 8 * (r >> 2) + 4 * hi; }
; #define SBAR() __builtin_amdgcn_sched_barrier(0)
; #define RESC(a) do { if (__any((a) < 1.f)) { if (hi == 0) al_l[r32] = (a); asm volatile("s_waitcnt lgkmcnt(0)" ::: "memory"); \
;     _Pragma("unroll") for (int dd = 0; dd < 2; ++dd) _Pragma("unroll") for (int r = 0; r < 16; ++r) o[dd][r] *= al_l[crow(r, hi)]; } } while (0)
; __device__ void phase_attn(const Params& p, char* lds) {
;     ...
;     pv_d0(o, vb0, pa0, pa1, pa2, pa3); at_partialSM(pB0, pB1, m_reg, alB, false);
;     __syncthreads(); RESC(alB);
;     at_finishSM(pB0, pB1, alB, l_reg, pa0, pa1, pa2, pa3); SBAR();
;     pv_d0(o, vb0 + AT_SHMV, pa0, pa1, pa2, pa3);
;     if (hi == 0) li_l[r32] = l_reg;
;     asm volatile("s_waitcnt lgkmcnt(0)" ::: "memory");
;     float rli[16];
; #pragma unroll
;     for (int r = 0; r < 16; ++r) rli[r] = __builtin_amdgcn_rcpf(li_l[crow(r, hi)]);
;     bf16_t* Gw = G1 + (row0 + qblk * 256 + wid * 32) * 1024 + h * 64 + r32;
;     bf16_t gin[32];
; #pragma unroll
;     for (int r = 0; r < 16; ++r) { gin[2 * r] = Gw[(size_t)crow(r, hi) * 1024]; gin[2 * r + 1] = Gw[(size_t)crow(r, hi) * 1024 + 32]; }
	ds_read_b64_tr_b16 v[148:149], v171 offset:49152
	ds_read_b64_tr_b16 v[150:151], v171 offset:51200
	ds_read_b64_tr_b16 v[152:153], v171 offset:53248
	ds_read_b64_tr_b16 v[154:155], v171 offset:55296
	ds_read_b64_tr_b16 v[156:157], v171 offset:57344
	ds_read_b64_tr_b16 v[158:159], v171 offset:59392
	ds_read_b64_tr_b16 v[216:217], v171 offset:61440
	ds_read_b64_tr_b16 v[218:219], v171 offset:63488
	ds_read_b64_tr_b16 v[220:221], v171 offset:49664
	ds_read_b64_tr_b16 v[222:223], v171 offset:51712
	ds_read_b64_tr_b16 v[224:225], v171 offset:53760
	ds_read_b64_tr_b16 v[226:227], v171 offset:55808
	s_waitcnt lgkmcnt(10)
	v_mfma_f32_32x32x16_bf16 v[0:15], v[104:107], v[148:151], v[0:15]
	s_waitcnt lgkmcnt(8)
	v_mfma_f32_32x32x16_bf16 v[0:15], v[108:111], v[152:155], v[0:15]
	ds_read_b64_tr_b16 v[236:237], v171 offset:57856
	ds_read_b64_tr_b16 v[238:239], v171 offset:59904
	ds_read_b64_tr_b16 v[240:241], v171 offset:61952
	ds_read_b64_tr_b16 v[242:243], v171 offset:64000
	s_waitcnt lgkmcnt(10)
	v_mfma_f32_32x32x16_bf16 v[0:15], v[112:115], v[156:159], v[0:15]
	s_waitcnt lgkmcnt(8)
	v_mfma_f32_32x32x16_bf16 v[0:15], v[116:119], v[216:219], v[0:15]
	s_waitcnt lgkmcnt(6)
	v_mfma_f32_32x32x16_bf16 v[16:31], v[104:107], v[220:223], v[16:31]
	s_waitcnt lgkmcnt(4)
	v_mfma_f32_32x32x16_bf16 v[16:31], v[108:111], v[224:227], v[16:31]
	s_waitcnt lgkmcnt(2)
	v_mfma_f32_32x32x16_bf16 v[16:31], v[112:115], v[236:239], v[16:31]
	s_waitcnt lgkmcnt(0)
	v_mfma_f32_32x32x16_bf16 v[16:31], v[116:119], v[240:243], v[16:31]
	s_cmp_lg_u32 s15, 0
	s_cbranch_scc1 .Lat_nobal
	s_barrier
.Lat_nobal:
	v_mov_b32_e32 v175, v173
	s_nop 1
	v_permlane32_swap_b32_e32 v173, v175
	v_add_f32_e32 v173, v173, v175
	ds_write_b32 v244, v173 offset:128
	s_waitcnt lgkmcnt(0)
	ds_read_b128 v[184:187], v245 offset:128
	ds_read_b128 v[188:191], v245 offset:160
	ds_read_b128 v[192:195], v245 offset:192
	ds_read_b128 v[196:199], v245 offset:224
	s_add_u32 s8, s28, 0x0
	s_addc_u32 s9, s29, 0
	global_load_ushort v32, v235, s[8:9] offset:0
	global_load_ushort v33, v235, s[8:9] offset:64
	global_load_ushort v34, v235, s[8:9] offset:2048
	global_load_ushort v35, v235, s[8:9] offset:2112
	s_add_u32 s8, s28, 0x1000
	s_addc_u32 s9, s29, 0
	global_load_ushort v36, v235, s[8:9] offset:0
	global_load_ushort v37, v235, s[8:9] offset:64
	global_load_ushort v38, v235, s[8:9] offset:2048
	global_load_ushort v39, v235, s[8:9] offset:2112
	s_add_u32 s8, s28, 0x4000
	s_addc_u32 s9, s29, 0
	global_load_ushort v40, v235, s[8:9] offset:0
	global_load_ushort v41, v235, s[8:9] offset:64
	global_load_ushort v42, v235, s[8:9] offset:2048
	global_load_ushort v43, v235, s[8:9] offset:2112
	s_add_u32 s8, s28, 0x5000
	s_addc_u32 s9, s29, 0
	global_load_ushort v44, v235, s[8:9] offset:0
	global_load_ushort v45, v235, s[8:9] offset:64
	global_load_ushort v46, v235, s[8:9] offset:2048
	global_load_ushort v47, v235, s[8:9] offset:2112
	s_add_u32 s8, s28, 0x8000
	s_addc_u32 s9, s29, 0
	global_load_ushort v48, v235, s[8:9] offset:0
	global_load_ushort v49, v235, s[8:9] offset:64
	global_load_ushort v50, v235, s[8:9] offset:2048
	global_load_ushort v51, v235, s[8:9] offset:2112
	s_add_u32 s8, s28, 0x9000
	s_addc_u32 s9, s29, 0
	global_load_ushort v52, v235, s[8:9] offset:0
	global_load_ushort v53, v235, s[8:9] offset:64
	global_load_ushort v54, v235, s[8:9] offset:2048
	global_load_ushort v55, v235, s[8:9] offset:2112
	s_add_u32 s8, s28, 0xc000
	s_addc_u32 s9, s29, 0
	global_load_ushort v56, v235, s[8:9] offset:0
	global_load_ushort v57, v235, s[8:9] offset:64
	global_load_ushort v58, v235, s[8:9] offset:2048
	global_load_ushort v59, v235, s[8:9] offset:2112
	s_add_u32 s8, s28, 0xd000
	s_addc_u32 s9, s29, 0
	global_load_ushort v60, v235, s[8:9] offset:0
	global_load_ushort v61, v235, s[8:9] offset:64
	global_load_ushort v62, v235, s[8:9] offset:2048
	global_load_ushort v63, v235, s[8:9] offset:2112
	s_waitcnt lgkmcnt(0)
	v_rcp_f32_e32 v184, v184
	v_rcp_f32_e32 v185, v185
	v_rcp_f32_e32 v186, v186
	v_rcp_f32_e32 v187, v187
	v_rcp_f32_e32 v188, v188
	v_rcp_f32_e32 v189, v189
	v_rcp_f32_e32 v190, v190
	v_rcp_f32_e32 v191, v191
	v_rcp_f32_e32 v192, v192
	v_rcp_f32_e32 v193, v193
	v_rcp_f32_e32 v194, v194
	v_rcp_f32_e32 v195, v195
	v_rcp_f32_e32 v196, v196
	v_rcp_f32_e32 v197, v197
	v_rcp_f32_e32 v198, v198
	v_rcp_f32_e32 v199, v199
	v_mul_f32_e32 v0, v0, v184
	v_mul_f32_e32 v16, v16, v184
	v_mul_f32_e32 v1, v1, v185
	v_mul_f32_e32 v17, v17, v185
	v_mul_f32_e32 v2, v2, v186
	v_mul_f32_e32 v18, v18, v186
	v_mul_f32_e32 v3, v3, v187
	v_mul_f32_e32 v19, v19, v187
	v_mul_f32_e32 v4, v4, v188
	v_mul_f32_e32 v20, v20, v188
	v_mul_f32_e32 v5, v5, v189
	v_mul_f32_e32 v21, v21, v189
	v_mul_f32_e32 v6, v6, v190
	v_mul_f32_e32 v22, v22, v190
	v_mul_f32_e32 v7, v7, v191
	v_mul_f32_e32 v23, v23, v191
	v_mul_f32_e32 v8, v8, v192
	v_mul_f32_e32 v24, v24, v192
	v_mul_f32_e32 v9, v9, v193
	v_mul_f32_e32 v25, v25, v193
	v_mul_f32_e32 v10, v10, v194
	v_mul_f32_e32 v26, v26, v194
	v_mul_f32_e32 v11, v11, v195
	v_mul_f32_e32 v27, v27, v195
	v_mul_f32_e32 v12, v12, v196
	v_mul_f32_e32 v28, v28, v196
	v_mul_f32_e32 v13, v13, v197
	v_mul_f32_e32 v29, v29, v197
	v_mul_f32_e32 v14, v14, v198
	v_mul_f32_e32 v30, v30, v198
	v_mul_f32_e32 v15, v15, v199
	v_mul_f32_e32 v31, v31, v199
	s_waitcnt vmcnt(0)
; __device__ __forceinline__ float bf2f(bf16_t u) { return __uint_as_float(((unsigned)u) << 16); }
; __device__ __forceinline__ bf16_t f2bf(float f) { return (bf16_t)(cvtpk(f, 0.f) & 0xffffu); }
; __device__ __forceinline__ int crow(int r, int hi) { return (r & 3) + 8 * (r >> 2) + 4 * hi; }
; __device__ __forceinline__ float sigmoidf_(float x) { return __builtin_amdgcn_rcpf(1.f + __expf(-x)); }
; __device__ void phase_attn(const Params& p, char* lds) {
;     ...
;     asm volatile("" ::: "memory");
; #pragma unroll
;     for (int r = 0; r < 16; ++r) {
;       const int orow = crow(r, hi);
; #pragma unroll
;       for (int d0 = 0; d0 < 2; ++d0) {
;         const float gt = bf2f(gin[2 * r + d0]);
;         Gw[(size_t)orow * 1024 + d0 * 32] = f2bf(o[d0][r] * rli[r] * gt * sigmoidf_(gt));
;       }
;     }
	v_lshlrev_b32_e32 v32, 16, v32
	v_lshlrev_b32_e32 v33, 16, v33
	v_lshlrev_b32_e32 v34, 16, v34
	v_lshlrev_b32_e32 v35, 16, v35
	v_lshlrev_b32_e32 v36, 16, v36
	v_lshlrev_b32_e32 v37, 16, v37
	v_lshlrev_b32_e32 v38, 16, v38
	v_lshlrev_b32_e32 v39, 16, v39
	v_mul_f32_e32 v64, 0xbfb8aa3b, v32
	v_mul_f32_e32 v65, 0xbfb8aa3b, v33
	v_mul_f32_e32 v66, 0xbfb8aa3b, v34
	v_mul_f32_e32 v67, 0xbfb8aa3b, v35
	v_mul_f32_e32 v68, 0xbfb8aa3b, v36
	v_mul_f32_e32 v69, 0xbfb8aa3b, v37
	v_mul_f32_e32 v70, 0xbfb8aa3b, v38
	v_mul_f32_e32 v71, 0xbfb8aa3b, v39
	v_exp_f32_e32 v64, v64
	v_exp_f32_e32 v65, v65
	v_exp_f32_e32 v66, v66
	v_exp_f32_e32 v67, v67
	v_exp_f32_e32 v68, v68
	v_exp_f32_e32 v69, v69
	v_exp_f32_e32 v70, v70
	v_exp_f32_e32 v71, v71
	v_add_f32_e32 v64, 1.0, v64
	v_add_f32_e32 v65, 1.0, v65
	v_add_f32_e32 v66, 1.0, v66
	v_add_f32_e32 v67, 1.0, v67
	v_add_f32_e32 v68, 1.0, v68
	v_add_f32_e32 v69, 1.0, v69
	v_add_f32_e32 v70, 1.0, v70
	v_add_f32_e32 v71, 1.0, v71
	v_rcp_f32_e32 v64, v64
	v_rcp_f32_e32 v65, v65
	v_rcp_f32_e32 v66, v66
	v_rcp_f32_e32 v67, v67
	v_rcp_f32_e32 v68, v68
	v_rcp_f32_e32 v69, v69
	v_rcp_f32_e32 v70, v70
	v_rcp_f32_e32 v71, v71
	v_mul_f32_e32 v0, v0, v32
	v_mul_f32_e32 v16, v16, v33
	v_mul_f32_e32 v1, v1, v34
	v_mul_f32_e32 v17, v17, v35
	v_mul_f32_e32 v2, v2, v36
	v_mul_f32_e32 v18, v18, v37
	v_mul_f32_e32 v3, v3, v38
	v_mul_f32_e32 v19, v19, v39
	v_mul_f32_e32 v0, v0, v64
	v_mul_f32_e32 v16, v16, v65
	v_mul_f32_e32 v1, v1, v66
	v_mul_f32_e32 v17, v17, v67
	v_mul_f32_e32 v2, v2, v68
	v_mul_f32_e32 v18, v18, v69
	v_mul_f32_e32 v3, v3, v70
	v_mul_f32_e32 v19, v19, v71
	v_cvt_pk_bf16_f32 v0, v0, v0
	v_cvt_pk_bf16_f32 v16, v16, v16
	v_cvt_pk_bf16_f32 v1, v1, v1
	v_cvt_pk_bf16_f32 v17, v17, v17
	v_cvt_pk_bf16_f32 v2, v2, v2
	v_cvt_pk_bf16_f32 v18, v18, v18
	v_cvt_pk_bf16_f32 v3, v3, v3
	v_cvt_pk_bf16_f32 v19, v19, v19
	s_add_u32 s8, s28, 0x0
	s_addc_u32 s9, s29, 0
	global_store_short v235, v0, s[8:9] offset:0
	global_store_short v235, v16, s[8:9] offset:64
	global_store_short v235, v1, s[8:9] offset:2048
	global_store_short v235, v17, s[8:9] offset:2112
	s_add_u32 s8, s28, 0x1000
	s_addc_u32 s9, s29, 0
	global_store_short v235, v2, s[8:9] offset:0
	global_store_short v235, v18, s[8:9] offset:64
	global_store_short v235, v3, s[8:9] offset:2048
	global_store_short v235, v19, s[8:9] offset:2112
	v_lshlrev_b32_e32 v40, 16, v40
	v_lshlrev_b32_e32 v41, 16, v41
	v_lshlrev_b32_e32 v42, 16, v42
	v_lshlrev_b32_e32 v43, 16, v43
	v_lshlrev_b32_e32 v44, 16, v44
	v_lshlrev_b32_e32 v45, 16, v45
	v_lshlrev_b32_e32 v46, 16, v46
	v_lshlrev_b32_e32 v47, 16, v47
	v_mul_f32_e32 v64, 0xbfb8aa3b, v40
	v_mul_f32_e32 v65, 0xbfb8aa3b, v41
	v_mul_f32_e32 v66, 0xbfb8aa3b, v42
	v_mul_f32_e32 v67, 0xbfb8aa3b, v43
	v_mul_f32_e32 v68, 0xbfb8aa3b, v44
	v_mul_f32_e32 v69, 0xbfb8aa3b, v45
	v_mul_f32_e32 v70, 0xbfb8aa3b, v46
	v_mul_f32_e32 v71, 0xbfb8aa3b, v47
	v_exp_f32_e32 v64, v64
	v_exp_f32_e32 v65, v65
	v_exp_f32_e32 v66, v66
	v_exp_f32_e32 v67, v67
	v_exp_f32_e32 v68, v68
	v_exp_f32_e32 v69, v69
	v_exp_f32_e32 v70, v70
	v_exp_f32_e32 v71, v71
	v_add_f32_e32 v64, 1.0, v64
	v_add_f32_e32 v65, 1.0, v65
	v_add_f32_e32 v66, 1.0, v66
	v_add_f32_e32 v67, 1.0, v67
	v_add_f32_e32 v68, 1.0, v68
	v_add_f32_e32 v69, 1.0, v69
	v_add_f32_e32 v70, 1.0, v70
	v_add_f32_e32 v71, 1.0, v71
	v_rcp_f32_e32 v64, v64
	v_rcp_f32_e32 v65, v65
	v_rcp_f32_e32 v66, v66
	v_rcp_f32_e32 v67, v67
	v_rcp_f32_e32 v68, v68
	v_rcp_f32_e32 v69, v69
	v_rcp_f32_e32 v70, v70
	v_rcp_f32_e32 v71, v71
	v_mul_f32_e32 v4, v4, v40
	v_mul_f32_e32 v20, v20, v41
	v_mul_f32_e32 v5, v5, v42
	v_mul_f32_e32 v21, v21, v43
	v_mul_f32_e32 v6, v6, v44
	v_mul_f32_e32 v22, v22, v45
	v_mul_f32_e32 v7, v7, v46
	v_mul_f32_e32 v23, v23, v47
	v_mul_f32_e32 v4, v4, v64
	v_mul_f32_e32 v20, v20, v65
	v_mul_f32_e32 v5, v5, v66
	v_mul_f32_e32 v21, v21, v67
	v_mul_f32_e32 v6, v6, v68
	v_mul_f32_e32 v22, v22, v69
	v_mul_f32_e32 v7, v7, v70
	v_mul_f32_e32 v23, v23, v71
	v_cvt_pk_bf16_f32 v4, v4, v4
	v_cvt_pk_bf16_f32 v20, v20, v20
	v_cvt_pk_bf16_f32 v5, v5, v5
	v_cvt_pk_bf16_f32 v21, v21, v21
	v_cvt_pk_bf16_f32 v6, v6, v6
	v_cvt_pk_bf16_f32 v22, v22, v22
	v_cvt_pk_bf16_f32 v7, v7, v7
	v_cvt_pk_bf16_f32 v23, v23, v23
	s_add_u32 s8, s28, 0x4000
	s_addc_u32 s9, s29, 0
	global_store_short v235, v4, s[8:9] offset:0
	global_store_short v235, v20, s[8:9] offset:64
	global_store_short v235, v5, s[8:9] offset:2048
	global_store_short v235, v21, s[8:9] offset:2112
	s_add_u32 s8, s28, 0x5000
	s_addc_u32 s9, s29, 0
	global_store_short v235, v6, s[8:9] offset:0
	global_store_short v235, v22, s[8:9] offset:64
	global_store_short v235, v7, s[8:9] offset:2048
	global_store_short v235, v23, s[8:9] offset:2112
	v_lshlrev_b32_e32 v48, 16, v48
	v_lshlrev_b32_e32 v49, 16, v49
	v_lshlrev_b32_e32 v50, 16, v50
	v_lshlrev_b32_e32 v51, 16, v51
	v_lshlrev_b32_e32 v52, 16, v52
	v_lshlrev_b32_e32 v53, 16, v53
	v_lshlrev_b32_e32 v54, 16, v54
	v_lshlrev_b32_e32 v55, 16, v55
	v_mul_f32_e32 v64, 0xbfb8aa3b, v48
	v_mul_f32_e32 v65, 0xbfb8aa3b, v49
	v_mul_f32_e32 v66, 0xbfb8aa3b, v50
	v_mul_f32_e32 v67, 0xbfb8aa3b, v51
	v_mul_f32_e32 v68, 0xbfb8aa3b, v52
	v_mul_f32_e32 v69, 0xbfb8aa3b, v53
	v_mul_f32_e32 v70, 0xbfb8aa3b, v54
	v_mul_f32_e32 v71, 0xbfb8aa3b, v55
	v_exp_f32_e32 v64, v64
	v_exp_f32_e32 v65, v65
	v_exp_f32_e32 v66, v66
	v_exp_f32_e32 v67, v67
	v_exp_f32_e32 v68, v68
	v_exp_f32_e32 v69, v69
	v_exp_f32_e32 v70, v70
	v_exp_f32_e32 v71, v71
	v_add_f32_e32 v64, 1.0, v64
	v_add_f32_e32 v65, 1.0, v65
	v_add_f32_e32 v66, 1.0, v66
	v_add_f32_e32 v67, 1.0, v67
	v_add_f32_e32 v68, 1.0, v68
	v_add_f32_e32 v69, 1.0, v69
	v_add_f32_e32 v70, 1.0, v70
; __device__ __forceinline__ float bf2f(bf16_t u) { return __uint_as_float(((unsigned)u) << 16); }
; __device__ __forceinline__ bf16_t f2bf(float f) { return (bf16_t)(cvtpk(f, 0.f) & 0xffffu); }
; __device__ __forceinline__ int crow(int r, int hi) { return (r & 3) + 8 * (r >> 2) + 4 * hi; }
; __device__ __forceinline__ float sigmoidf_(float x) { return __builtin_amdgcn_rcpf(1.f + __expf(-x)); }
; __device__ __forceinline__ void at_partialSM(f32x16& p0, f32x16& p1, float& m_reg, float& alpha, bool force) {
;     ...
;   if (__builtin_expect(!force && __all(pm <= AT_THR * 1.4426950408889634f), 1)) { alpha = 1.f; }
;   else {
;     const float dlt = force ? pm : fmaxf(pm, 0.f);
;     alpha = force ? 1.f : __builtin_amdgcn_exp2f(-dlt); m_reg += dlt;
; #pragma unroll
;     for (int r = 0; r < 16; ++r) { p0[r] -= dlt; p1[r] -= dlt; }
;   }
; __device__ void phase_attn(const Params& p, char* lds) {
;     ...
;     for (int r = 0; r < 16; ++r) {
;       const int orow = crow(r, hi);
; #pragma unroll
;       for (int d0 = 0; d0 < 2; ++d0) {
;         const float gt = bf2f(gin[2 * r + d0]);
;         Gw[(size_t)orow * 1024 + d0 * 32] = f2bf(o[d0][r] * rli[r] * gt * sigmoidf_(gt));
;       }
;     }
	v_add_f32_e32 v71, 1.0, v71
	v_rcp_f32_e32 v64, v64
	v_rcp_f32_e32 v65, v65
	v_rcp_f32_e32 v66, v66
	v_rcp_f32_e32 v67, v67
	v_rcp_f32_e32 v68, v68
	v_rcp_f32_e32 v69, v69
	v_rcp_f32_e32 v70, v70
	v_rcp_f32_e32 v71, v71
	v_mul_f32_e32 v8, v8, v48
	v_mul_f32_e32 v24, v24, v49
	v_mul_f32_e32 v9, v9, v50
	v_mul_f32_e32 v25, v25, v51
	v_mul_f32_e32 v10, v10, v52
	v_mul_f32_e32 v26, v26, v53
	v_mul_f32_e32 v11, v11, v54
	v_mul_f32_e32 v27, v27, v55
	v_mul_f32_e32 v8, v8, v64
	v_mul_f32_e32 v24, v24, v65
	v_mul_f32_e32 v9, v9, v66
	v_mul_f32_e32 v25, v25, v67
	v_mul_f32_e32 v10, v10, v68
	v_mul_f32_e32 v26, v26, v69
	v_mul_f32_e32 v11, v11, v70
	v_mul_f32_e32 v27, v27, v71
	v_cvt_pk_bf16_f32 v8, v8, v8
	v_cvt_pk_bf16_f32 v24, v24, v24
	v_cvt_pk_bf16_f32 v9, v9, v9
	v_cvt_pk_bf16_f32 v25, v25, v25
	v_cvt_pk_bf16_f32 v10, v10, v10
	v_cvt_pk_bf16_f32 v26, v26, v26
	v_cvt_pk_bf16_f32 v11, v11, v11
	v_cvt_pk_bf16_f32 v27, v27, v27
	s_add_u32 s8, s28, 0x8000
	s_addc_u32 s9, s29, 0
	global_store_short v235, v8, s[8:9] offset:0
	global_store_short v235, v24, s[8:9] offset:64
	global_store_short v235, v9, s[8:9] offset:2048
	global_store_short v235, v25, s[8:9] offset:2112
	s_add_u32 s8, s28, 0x9000
	s_addc_u32 s9, s29, 0
	global_store_short v235, v10, s[8:9] offset:0
	global_store_short v235, v26, s[8:9] offset:64
	global_store_short v235, v11, s[8:9] offset:2048
	global_store_short v235, v27, s[8:9] offset:2112
	v_lshlrev_b32_e32 v56, 16, v56
	v_lshlrev_b32_e32 v57, 16, v57
	v_lshlrev_b32_e32 v58, 16, v58
	v_lshlrev_b32_e32 v59, 16, v59
	v_lshlrev_b32_e32 v60, 16, v60
	v_lshlrev_b32_e32 v61, 16, v61
	v_lshlrev_b32_e32 v62, 16, v62
	v_lshlrev_b32_e32 v63, 16, v63
	v_mul_f32_e32 v64, 0xbfb8aa3b, v56
	v_mul_f32_e32 v65, 0xbfb8aa3b, v57
	v_mul_f32_e32 v66, 0xbfb8aa3b, v58
	v_mul_f32_e32 v67, 0xbfb8aa3b, v59
	v_mul_f32_e32 v68, 0xbfb8aa3b, v60
	v_mul_f32_e32 v69, 0xbfb8aa3b, v61
	v_mul_f32_e32 v70, 0xbfb8aa3b, v62
	v_mul_f32_e32 v71, 0xbfb8aa3b, v63
	v_exp_f32_e32 v64, v64
	v_exp_f32_e32 v65, v65
	v_exp_f32_e32 v66, v66
	v_exp_f32_e32 v67, v67
	v_exp_f32_e32 v68, v68
	v_exp_f32_e32 v69, v69
	v_exp_f32_e32 v70, v70
	v_exp_f32_e32 v71, v71
	v_add_f32_e32 v64, 1.0, v64
	v_add_f32_e32 v65, 1.0, v65
	v_add_f32_e32 v66, 1.0, v66
	v_add_f32_e32 v67, 1.0, v67
	v_add_f32_e32 v68, 1.0, v68
	v_add_f32_e32 v69, 1.0, v69
	v_add_f32_e32 v70, 1.0, v70
	v_add_f32_e32 v71, 1.0, v71
	v_rcp_f32_e32 v64, v64
	v_rcp_f32_e32 v65, v65
	v_rcp_f32_e32 v66, v66
	v_rcp_f32_e32 v67, v67
	v_rcp_f32_e32 v68, v68
	v_rcp_f32_e32 v69, v69
	v_rcp_f32_e32 v70, v70
	v_rcp_f32_e32 v71, v71
	v_mul_f32_e32 v12, v12, v56
	v_mul_f32_e32 v28, v28, v57
	v_mul_f32_e32 v13, v13, v58
	v_mul_f32_e32 v29, v29, v59
	v_mul_f32_e32 v14, v14, v60
	v_mul_f32_e32 v30, v30, v61
	v_mul_f32_e32 v15, v15, v62
	v_mul_f32_e32 v31, v31, v63
	v_mul_f32_e32 v12, v12, v64
	v_mul_f32_e32 v28, v28, v65
	v_mul_f32_e32 v13, v13, v66
	v_mul_f32_e32 v29, v29, v67
	v_mul_f32_e32 v14, v14, v68
	v_mul_f32_e32 v30, v30, v69
	v_mul_f32_e32 v15, v15, v70
	v_mul_f32_e32 v31, v31, v71
	v_cvt_pk_bf16_f32 v12, v12, v12
	v_cvt_pk_bf16_f32 v28, v28, v28
	v_cvt_pk_bf16_f32 v13, v13, v13
	v_cvt_pk_bf16_f32 v29, v29, v29
	v_cvt_pk_bf16_f32 v14, v14, v14
	v_cvt_pk_bf16_f32 v30, v30, v30
	v_cvt_pk_bf16_f32 v15, v15, v15
	v_cvt_pk_bf16_f32 v31, v31, v31
	s_add_u32 s8, s28, 0xc000
	s_addc_u32 s9, s29, 0
	global_store_short v235, v12, s[8:9] offset:0
	global_store_short v235, v28, s[8:9] offset:64
	global_store_short v235, v13, s[8:9] offset:2048
	global_store_short v235, v29, s[8:9] offset:2112
	s_add_u32 s8, s28, 0xd000
	s_addc_u32 s9, s29, 0
	global_store_short v235, v14, s[8:9] offset:0
	global_store_short v235, v30, s[8:9] offset:64
	global_store_short v235, v15, s[8:9] offset:2048
	global_store_short v235, v31, s[8:9] offset:2112
	s_add_i32 s12, s12, s33
	s_cmpk_lt_u32 s12, 0x200
	s_cbranch_scc1 .Lat_item
	s_branch .Lat_done
.Lat_rare0:
	v_max_f32_e32 v174, 0, v174
	v_sub_f32_e32 v175, 0, v174
	v_exp_f32_e32 v181, v175
	v_add_f32_e32 v172, v172, v174
	v_sub_f32_e32 v32, v32, v174
	v_sub_f32_e32 v48, v48, v174
	v_sub_f32_e32 v33, v33, v174
	v_sub_f32_e32 v49, v49, v174
	v_sub_f32_e32 v34, v34, v174
	v_sub_f32_e32 v50, v50, v174
	v_sub_f32_e32 v35, v35, v174
	v_sub_f32_e32 v51, v51, v174
	v_sub_f32_e32 v36, v36, v174
	v_sub_f32_e32 v52, v52, v174
	v_sub_f32_e32 v37, v37, v174
	v_sub_f32_e32 v53, v53, v174
	v_sub_f32_e32 v38, v38, v174
	v_sub_f32_e32 v54, v54, v174
	v_sub_f32_e32 v39, v39, v174
	v_sub_f32_e32 v55, v55, v174
	v_sub_f32_e32 v40, v40, v174
	v_sub_f32_e32 v56, v56, v174
	v_sub_f32_e32 v41, v41, v174
	v_sub_f32_e32 v57, v57, v174
	v_sub_f32_e32 v42, v42, v174
	v_sub_f32_e32 v58, v58, v174
	v_sub_f32_e32 v43, v43, v174
	v_sub_f32_e32 v59, v59, v174
	v_sub_f32_e32 v44, v44, v174
	v_sub_f32_e32 v60, v60, v174
	v_sub_f32_e32 v45, v45, v174
	v_sub_f32_e32 v61, v61, v174
	v_sub_f32_e32 v46, v46, v174
	v_sub_f32_e32 v62, v62, v174
	v_sub_f32_e32 v47, v47, v174
	v_sub_f32_e32 v63, v63, v174
	v_sub_f32_e32 v64, 0, v172
	v_sub_f32_e32 v65, 0, v172
	v_sub_f32_e32 v66, 0, v172
	v_sub_f32_e32 v67, 0, v172
	v_sub_f32_e32 v68, 0, v172
	v_sub_f32_e32 v69, 0, v172
	v_sub_f32_e32 v70, 0, v172
	v_sub_f32_e32 v71, 0, v172
	v_sub_f32_e32 v72, 0, v172
	v_sub_f32_e32 v73, 0, v172
	v_sub_f32_e32 v74, 0, v172
	v_sub_f32_e32 v75, 0, v172
	v_sub_f32_e32 v76, 0, v172
	v_sub_f32_e32 v77, 0, v172
	v_sub_f32_e32 v78, 0, v172
	v_sub_f32_e32 v79, 0, v172
	v_mul_f32_e32 v173, v173, v181
	ds_write_b32 v244, v181
	s_waitcnt lgkmcnt(0)
	ds_read_b128 v[184:187], v245 offset:0
	ds_read_b128 v[188:191], v245 offset:32
	ds_read_b128 v[192:195], v245 offset:64
	ds_read_b128 v[196:199], v245 offset:96
	s_waitcnt lgkmcnt(0)
	v_mul_f32_e32 v0, v0, v184
	v_mul_f32_e32 v16, v16, v184
	v_mul_f32_e32 v1, v1, v185
	v_mul_f32_e32 v17, v17, v185
	v_mul_f32_e32 v2, v2, v186
	v_mul_f32_e32 v18, v18, v186
	v_mul_f32_e32 v3, v3, v187
	v_mul_f32_e32 v19, v19, v187
	v_mul_f32_e32 v4, v4, v188
	v_mul_f32_e32 v20, v20, v188
	v_mul_f32_e32 v5, v5, v189
	v_mul_f32_e32 v21, v21, v189
	v_mul_f32_e32 v6, v6, v190
	v_mul_f32_e32 v22, v22, v190
	v_mul_f32_e32 v7, v7, v191
	v_mul_f32_e32 v23, v23, v191
	v_mul_f32_e32 v8, v8, v192
	v_mul_f32_e32 v24, v24, v192
	v_mul_f32_e32 v9, v9, v193
	v_mul_f32_e32 v25, v25, v193
	v_mul_f32_e32 v10, v10, v194
	v_mul_f32_e32 v26, v26, v194
	v_mul_f32_e32 v11, v11, v195
	v_mul_f32_e32 v27, v27, v195
	v_mul_f32_e32 v12, v12, v196
	v_mul_f32_e32 v28, v28, v196
	v_mul_f32_e32 v13, v13, v197
	v_mul_f32_e32 v29, v29, v197
	v_mul_f32_e32 v14, v14, v198
	v_mul_f32_e32 v30, v30, v198
	v_mul_f32_e32 v15, v15, v199
	v_mul_f32_e32 v31, v31, v199
	s_branch .Lat_rare0_back

; __global__ __launch_bounds__(NTHR, 1) void fwd_megakernel(Params p) {
;     ...
;   phase_attn(p, lds);
;   grid.sync();
.Lat_done:
.LBB0_1020:
	s_barrier
	s_and_saveexec_b64 s[4:5], s[56:57]
	s_cbranch_execz .LBB0_1030
	buffer_wbl2 sc1
	s_waitcnt vmcnt(0)
	s_load_dwordx2 s[6:7], s[88:89], 0x58
	v_mov_b32_e32 v2, 0
	s_mov_b64 s[8:9], exec
	v_mbcnt_lo_u32_b32 v1, s8, 0
	v_mbcnt_hi_u32_b32 v1, s9, v1
	s_waitcnt lgkmcnt(0)
	global_load_dword v0, v2, s[6:7] offset:40
	v_cmp_eq_u32_e32 vcc, 0, v1
	s_and_saveexec_b64 s[10:11], vcc
	s_cbranch_execz .LBB0_1023
	s_bcnt1_i32_b64 s0, s[8:9]
	v_mov_b32_e32 v3, s0
	global_atomic_add v3, v2, v3, s[6:7] offset:32 sc0
